# v70 + no non-MFMA VALU in K-loops (v83) + redundant lgkmcnt(0) removed at MFMA heads (v66): least-work stack
# baseline (speedup 1.0000x reference)
; #define PG8_STAGE(bufoff, gbase, voff) do { _Pragma("unroll") for (int _i = 0; _i < 2; ++_i) \
;         __builtin_amdgcn_global_load_lds((const unsigned*)((const char*)(gbase) + (voff)[_i]), (PG8_LAS unsigned*)(lds + (bufoff) + ldsw + _i * 8192), 16, 0, 0); } while (0)
; #define PG8_LDA(dst, b, h) do { _Pragma("unroll") for (int m = 0; m < 4; ++m) _Pragma("unroll") for (int k = 0; k < 2; ++k) dst[m][k] = *(const PG8_LAS bf16x8*)(lds + PG8_SA(b, h) + aoff + m * 2048 + k * 1024); } while (0)
; #define PG8_LDB(dst, b, h) do { _Pragma("unroll") for (int n = 0; n < 2; ++n) _Pragma("unroll") for (int k = 0; k < 2; ++k) dst[n][k] = *(const PG8_LAS bf16x8*)(lds + PG8_SB(b, h) + boff + n * 2048 + k * 1024); } while (0)
; #define PG8_MMA(ai, bj, At, Bt) do { __builtin_amdgcn_s_setprio(1); _Pragma("unroll") for (int m = 0; m < 4; ++m) _Pragma("unroll") for (int n = 0; n < 2; ++n) _Pragma("unroll") for (int k = 0; k < 2; ++k) \
;         acc[ai][bj][m][n] = __builtin_amdgcn_mfma_f32_16x16x32_bf16(Bt[n][k], At[m][k], acc[ai][bj][m][n], 0, 0, 0); __builtin_amdgcn_s_setprio(0); } while (0)
; #define PG8_WAIT_V(n) asm volatile("s_waitcnt vmcnt(" #n ")" ::: "memory")
; #define PG8_WAIT_L(n) asm volatile("s_waitcnt lgkmcnt(" #n ")" ::: "memory")
; template <class Epi, class Sched, bool ALIGN_EPI = false, bool SP2 = false>
; __device__ __forceinline__ void gemm_phase(PG8_LAS unsigned char* lds, const Gemm g, const Sched& S, const Epi& E) {
;     ...
;             const bool last = (t == nt - 2);
;             const char* a1 = cA + (size_t)(t + 1) * kstep;
;             const char* a2 = last ? nA : cA + (size_t)(t + 2) * kstep; const char* b2 = last ? nB : cB + (size_t)(t + 2) * kstep;
;             const char* a3 = a2 + kstep; const char* b3 = b2 + kstep;
;             if (last && has_next) S.a_ready(nxt);
;             if constexpr (SP2) {
;             PG8_LDB(B0, 0, 0); PG8_LDB(B1, 0, 1); PG8_SCHED; PG8_LDA(At, 0, 0); PG8_STAGE(PG8_SA(1, 1), a1 + hstep, voffA);
;             PG8_WAIT_V(8); PG8_WAIT_L(0); PG8_BAR; PG8_MMA(0, 0, At, B0); PG8_MMA(0, 1, At, B1); PG8_BAR; PG8_SCHED;
;             PG8_LDA(At, 0, 1); PG8_STAGE(PG8_SB(0, 0), b2, voffB); PG8_STAGE(PG8_SB(0, 1), b2 + hstep, voffB); PG8_STAGE(PG8_SA(0, 0), a2, voffA);
;             PG8_WAIT_V(8); PG8_WAIT_L(0); PG8_BAR; PG8_MMA(1, 0, At, B0); PG8_MMA(1, 1, At, B1); PG8_BAR; PG8_SCHED;
.LBB0_139:
	s_add_u32 s36, s30, 0xfff80080
	s_addc_u32 s37, s31, -1
	s_add_i32 s70, 0, 0x10000
	s_cmp_eq_u32 s69, 28
	s_cselect_b32 s39, s25, s37
	s_cselect_b32 s38, s45, s36
	s_cselect_b32 s37, s23, s68
	s_cselect_b32 s36, s66, s67
	s_add_i32 s75, 0, 0x14000
	ds_read_b128 v[152:155], v244
	ds_read_b128 v[166:169], v244 offset:1024
	ds_read_b128 v[170:173], v244 offset:2048
	ds_read_b128 v[174:177], v244 offset:3072
	ds_read_b128 v[178:181], v245
	ds_read_b128 v[182:185], v245 offset:1024
	ds_read_b128 v[186:189], v245 offset:2048
	ds_read_b128 v[190:193], v245 offset:3072
	s_add_u32 s98, s30, 0xfff80000
	s_addc_u32 s99, s31, -1
	s_mov_b32 m0, s57
	s_nop 0
	global_load_lds_dwordx4 v138, s[98:99]
	s_mov_b32 m0, s58
	s_nop 0
	global_load_lds_dwordx4 v140, s[98:99]
	s_add_i32 m0, s53, 0xc000
	ds_read_b128 v[200:203], v151
	ds_read_b128 v[204:207], v151 offset:1024
	ds_read_b128 v[208:211], v151 offset:2048
	ds_read_b128 v[212:215], v151 offset:3072
	ds_read_b128 v[216:219], v151 offset:4096
	ds_read_b128 v[220:223], v151 offset:5120
	ds_read_b128 v[224:227], v151 offset:6144
	ds_read_b128 v[228:231], v151 offset:7168
	global_load_lds_dwordx4 v138, s[30:31]
	s_add_i32 m0, s53, 0xe000
	s_nop 0
	global_load_lds_dwordx4 v140, s[30:31]
	s_waitcnt vmcnt(8)
	s_waitcnt lgkmcnt(0)
	s_barrier
	v_mfma_f32_16x16x32_bf16 v[126:129], v[152:155], v[200:203], v[126:129]
	v_mfma_f32_16x16x32_bf16 v[122:125], v[170:173], v[200:203], v[122:125]
	v_mfma_f32_16x16x32_bf16 v[110:113], v[152:155], v[208:211], v[110:113]
	v_mfma_f32_16x16x32_bf16 v[106:109], v[170:173], v[208:211], v[106:109]
	v_mfma_f32_16x16x32_bf16 v[94:97], v[152:155], v[216:219], v[94:97]
	v_mfma_f32_16x16x32_bf16 v[90:93], v[170:173], v[216:219], v[90:93]
	v_mfma_f32_16x16x32_bf16 v[78:81], v[152:155], v[224:227], v[78:81]
	v_mfma_f32_16x16x32_bf16 v[74:77], v[170:173], v[224:227], v[74:77]
	v_mfma_f32_16x16x32_bf16 v[126:129], v[166:169], v[204:207], v[126:129]
	v_mfma_f32_16x16x32_bf16 v[122:125], v[174:177], v[204:207], v[122:125]
	v_mfma_f32_16x16x32_bf16 v[110:113], v[166:169], v[212:215], v[110:113]
	v_mfma_f32_16x16x32_bf16 v[106:109], v[174:177], v[212:215], v[106:109]
	v_mfma_f32_16x16x32_bf16 v[94:97], v[166:169], v[220:223], v[94:97]
	v_mfma_f32_16x16x32_bf16 v[90:93], v[174:177], v[220:223], v[90:93]
	v_mfma_f32_16x16x32_bf16 v[78:81], v[166:169], v[228:231], v[78:81]
	v_mfma_f32_16x16x32_bf16 v[74:77], v[174:177], v[228:231], v[74:77]
	v_mfma_f32_16x16x32_bf16 v[118:121], v[178:181], v[200:203], v[118:121]
	v_mfma_f32_16x16x32_bf16 v[114:117], v[186:189], v[200:203], v[114:117]
	v_mfma_f32_16x16x32_bf16 v[102:105], v[178:181], v[208:211], v[102:105]
	v_mfma_f32_16x16x32_bf16 v[98:101], v[186:189], v[208:211], v[98:101]
	v_mfma_f32_16x16x32_bf16 v[86:89], v[178:181], v[216:219], v[86:89]
	v_mfma_f32_16x16x32_bf16 v[82:85], v[186:189], v[216:219], v[82:85]
	v_mfma_f32_16x16x32_bf16 v[70:73], v[178:181], v[224:227], v[70:73]
	v_mfma_f32_16x16x32_bf16 v[66:69], v[186:189], v[224:227], v[66:69]
	v_mfma_f32_16x16x32_bf16 v[118:121], v[182:185], v[204:207], v[118:121]
	v_mfma_f32_16x16x32_bf16 v[114:117], v[190:193], v[204:207], v[114:117]
	v_mfma_f32_16x16x32_bf16 v[102:105], v[182:185], v[212:215], v[102:105]
	v_mfma_f32_16x16x32_bf16 v[98:101], v[190:193], v[212:215], v[98:101]
	v_mfma_f32_16x16x32_bf16 v[86:89], v[182:185], v[220:223], v[86:89]
	v_mfma_f32_16x16x32_bf16 v[82:85], v[190:193], v[220:223], v[82:85]
	v_mfma_f32_16x16x32_bf16 v[70:73], v[182:185], v[228:231], v[70:73]
	v_mfma_f32_16x16x32_bf16 v[66:69], v[190:193], v[228:231], v[66:69]
	s_barrier
	s_add_i32 s70, s70, s52
	s_mov_b32 m0, s70
	ds_read_b128 v[200:203], v151 offset:16384
	ds_read_b128 v[204:207], v151 offset:17408
	ds_read_b128 v[208:211], v151 offset:18432
	ds_read_b128 v[212:215], v151 offset:19456
	ds_read_b128 v[216:219], v151 offset:20480
	ds_read_b128 v[220:223], v151 offset:21504
	ds_read_b128 v[224:227], v151 offset:22528
	ds_read_b128 v[228:231], v151 offset:23552
	global_load_lds_dwordx4 v158, s[36:37]
	s_add_i32 m0, s70, 0x2000
	s_add_u32 s70, s36, 0x80000
	s_addc_u32 s71, s37, 0
	s_add_i32 s75, s75, s52
	global_load_lds_dwordx4 v134, s[36:37]
	s_mov_b32 m0, s75
	s_nop 0
	global_load_lds_dwordx4 v158, s[70:71]
	s_add_i32 m0, s75, 0x2000
	s_nop 0
	global_load_lds_dwordx4 v134, s[70:71]
	s_waitcnt vmcnt(6)
	s_waitcnt lgkmcnt(0)
	s_barrier
	v_mfma_f32_16x16x32_bf16 v[62:65], v[152:155], v[200:203], v[62:65]
	v_mfma_f32_16x16x32_bf16 v[58:61], v[170:173], v[200:203], v[58:61]
	v_mfma_f32_16x16x32_bf16 v[46:49], v[152:155], v[208:211], v[46:49]
	v_mfma_f32_16x16x32_bf16 v[42:45], v[170:173], v[208:211], v[42:45]
	v_mfma_f32_16x16x32_bf16 v[30:33], v[152:155], v[216:219], v[30:33]
	v_mfma_f32_16x16x32_bf16 v[26:29], v[170:173], v[216:219], v[26:29]
	v_mfma_f32_16x16x32_bf16 v[14:17], v[152:155], v[224:227], v[14:17]
	v_mfma_f32_16x16x32_bf16 v[10:13], v[170:173], v[224:227], v[10:13]
	v_mfma_f32_16x16x32_bf16 v[62:65], v[166:169], v[204:207], v[62:65]
	v_mfma_f32_16x16x32_bf16 v[58:61], v[174:177], v[204:207], v[58:61]
	v_mfma_f32_16x16x32_bf16 v[46:49], v[166:169], v[212:215], v[46:49]
	v_mfma_f32_16x16x32_bf16 v[42:45], v[174:177], v[212:215], v[42:45]
	v_mfma_f32_16x16x32_bf16 v[30:33], v[166:169], v[220:223], v[30:33]
	v_mfma_f32_16x16x32_bf16 v[26:29], v[174:177], v[220:223], v[26:29]
	v_mfma_f32_16x16x32_bf16 v[14:17], v[166:169], v[228:231], v[14:17]
	v_mfma_f32_16x16x32_bf16 v[10:13], v[174:177], v[228:231], v[10:13]
	v_mfma_f32_16x16x32_bf16 v[54:57], v[178:181], v[200:203], v[54:57]
	v_mfma_f32_16x16x32_bf16 v[50:53], v[186:189], v[200:203], v[50:53]
	v_mfma_f32_16x16x32_bf16 v[38:41], v[178:181], v[208:211], v[38:41]
	v_mfma_f32_16x16x32_bf16 v[34:37], v[186:189], v[208:211], v[34:37]
	v_mfma_f32_16x16x32_bf16 v[22:25], v[178:181], v[216:219], v[22:25]
	v_mfma_f32_16x16x32_bf16 v[18:21], v[186:189], v[216:219], v[18:21]
	v_mfma_f32_16x16x32_bf16 v[6:9], v[178:181], v[224:227], v[6:9]
	v_mfma_f32_16x16x32_bf16 v[2:5], v[186:189], v[224:227], v[2:5]
	v_mfma_f32_16x16x32_bf16 v[54:57], v[182:185], v[204:207], v[54:57]
	v_mfma_f32_16x16x32_bf16 v[50:53], v[190:193], v[204:207], v[50:53]
	v_mfma_f32_16x16x32_bf16 v[38:41], v[182:185], v[212:215], v[38:41]
	v_mfma_f32_16x16x32_bf16 v[34:37], v[190:193], v[212:215], v[34:37]
	v_mfma_f32_16x16x32_bf16 v[22:25], v[182:185], v[220:223], v[22:25]
	v_mfma_f32_16x16x32_bf16 v[18:21], v[190:193], v[220:223], v[18:21]
	v_mfma_f32_16x16x32_bf16 v[6:9], v[182:185], v[228:231], v[6:9]
	v_mfma_f32_16x16x32_bf16 v[2:5], v[190:193], v[228:231], v[2:5]
	s_barrier
; #define PG8_STAGE(bufoff, gbase, voff) do { _Pragma("unroll") for (int _i = 0; _i < 2; ++_i) \
;         __builtin_amdgcn_global_load_lds((const unsigned*)((const char*)(gbase) + (voff)[_i]), (PG8_LAS unsigned*)(lds + (bufoff) + ldsw + _i * 8192), 16, 0, 0); } while (0)
; #define PG8_LDA(dst, b, h) do { _Pragma("unroll") for (int m = 0; m < 4; ++m) _Pragma("unroll") for (int k = 0; k < 2; ++k) dst[m][k] = *(const PG8_LAS bf16x8*)(lds + PG8_SA(b, h) + aoff + m * 2048 + k * 1024); } while (0)
; #define PG8_LDB(dst, b, h) do { _Pragma("unroll") for (int n = 0; n < 2; ++n) _Pragma("unroll") for (int k = 0; k < 2; ++k) dst[n][k] = *(const PG8_LAS bf16x8*)(lds + PG8_SB(b, h) + boff + n * 2048 + k * 1024); } while (0)
; #define PG8_MMA(ai, bj, At, Bt) do { __builtin_amdgcn_s_setprio(1); _Pragma("unroll") for (int m = 0; m < 4; ++m) _Pragma("unroll") for (int n = 0; n < 2; ++n) _Pragma("unroll") for (int k = 0; k < 2; ++k) \
;         acc[ai][bj][m][n] = __builtin_amdgcn_mfma_f32_16x16x32_bf16(Bt[n][k], At[m][k], acc[ai][bj][m][n], 0, 0, 0); __builtin_amdgcn_s_setprio(0); } while (0)
; #define PG8_WAIT_V(n) asm volatile("s_waitcnt vmcnt(" #n ")" ::: "memory")
; #define PG8_WAIT_L(n) asm volatile("s_waitcnt lgkmcnt(" #n ")" ::: "memory")
; #define PG8_BAR __builtin_amdgcn_s_barrier()
; #define PG8_SCHED __builtin_amdgcn_sched_barrier(0)
; template <class Epi, class Sched, bool ALIGN_EPI = false, bool SP2 = false>
; __device__ __forceinline__ void gemm_phase(PG8_LAS unsigned char* lds, const Gemm g, const Sched& S, const Epi& E) {
;     ...
;             PG8_LDB(B0, 1, 0); PG8_LDB(B1, 1, 1); PG8_SCHED; PG8_LDA(At, 1, 0); PG8_STAGE(PG8_SA(0, 1), a2 + hstep, voffA);
;             PG8_WAIT_V(8); PG8_WAIT_L(0); PG8_BAR; PG8_MMA(0, 0, At, B0); PG8_MMA(0, 1, At, B1); PG8_BAR; PG8_SCHED;
;             PG8_LDA(At, 1, 1); PG8_STAGE(PG8_SB(1, 0), b3, voffB); PG8_STAGE(PG8_SB(1, 1), b3 + hstep, voffB); PG8_STAGE(PG8_SA(1, 0), a3, voffA);
;             PG8_WAIT_V(8); PG8_WAIT_L(0); PG8_BAR; PG8_MMA(1, 0, At, B0); PG8_MMA(1, 1, At, B1); PG8_BAR; PG8_SCHED;
	s_add_i32 s70, 0, 0x18000
	s_add_i32 s71, 0, 0x1c000
	ds_read_b128 v[152:155], v246
	ds_read_b128 v[166:169], v246 offset:1024
	ds_read_b128 v[170:173], v246 offset:2048
	ds_read_b128 v[174:177], v246 offset:3072
	ds_read_b128 v[178:181], v247
	ds_read_b128 v[182:185], v247 offset:1024
	ds_read_b128 v[186:189], v247 offset:2048
	ds_read_b128 v[190:193], v247 offset:3072
	s_mov_b32 m0, s53
	s_nop 0
	global_load_lds_dwordx4 v130, s[38:39]
	s_mov_b32 m0, s54
	s_nop 0
	global_load_lds_dwordx4 v132, s[38:39]
	s_add_u32 s38, s38, 0x80000
	s_addc_u32 s39, s39, 0
	s_mov_b32 m0, s55
	ds_read_b128 v[200:203], v151 offset:32768
	ds_read_b128 v[204:207], v151 offset:33792
	ds_read_b128 v[208:211], v151 offset:34816
	ds_read_b128 v[212:215], v151 offset:35840
	ds_read_b128 v[216:219], v151 offset:36864
	ds_read_b128 v[220:223], v151 offset:37888
	ds_read_b128 v[224:227], v151 offset:38912
	ds_read_b128 v[228:231], v151 offset:39936
	global_load_lds_dwordx4 v130, s[38:39]
	s_mov_b32 m0, s56
	s_nop 0
	global_load_lds_dwordx4 v132, s[38:39]
	s_waitcnt vmcnt(8)
	s_waitcnt lgkmcnt(0)
	s_barrier
	v_mfma_f32_16x16x32_bf16 v[126:129], v[152:155], v[200:203], v[126:129]
	v_mfma_f32_16x16x32_bf16 v[122:125], v[170:173], v[200:203], v[122:125]
	v_mfma_f32_16x16x32_bf16 v[110:113], v[152:155], v[208:211], v[110:113]
	v_mfma_f32_16x16x32_bf16 v[106:109], v[170:173], v[208:211], v[106:109]
	v_mfma_f32_16x16x32_bf16 v[94:97], v[152:155], v[216:219], v[94:97]
	v_mfma_f32_16x16x32_bf16 v[90:93], v[170:173], v[216:219], v[90:93]
	v_mfma_f32_16x16x32_bf16 v[78:81], v[152:155], v[224:227], v[78:81]
	v_mfma_f32_16x16x32_bf16 v[74:77], v[170:173], v[224:227], v[74:77]
	v_mfma_f32_16x16x32_bf16 v[126:129], v[166:169], v[204:207], v[126:129]
	v_mfma_f32_16x16x32_bf16 v[122:125], v[174:177], v[204:207], v[122:125]
	v_mfma_f32_16x16x32_bf16 v[110:113], v[166:169], v[212:215], v[110:113]
	v_mfma_f32_16x16x32_bf16 v[106:109], v[174:177], v[212:215], v[106:109]
	v_mfma_f32_16x16x32_bf16 v[94:97], v[166:169], v[220:223], v[94:97]
	v_mfma_f32_16x16x32_bf16 v[90:93], v[174:177], v[220:223], v[90:93]
	v_mfma_f32_16x16x32_bf16 v[78:81], v[166:169], v[228:231], v[78:81]
	v_mfma_f32_16x16x32_bf16 v[74:77], v[174:177], v[228:231], v[74:77]
	v_mfma_f32_16x16x32_bf16 v[118:121], v[178:181], v[200:203], v[118:121]
	v_mfma_f32_16x16x32_bf16 v[114:117], v[186:189], v[200:203], v[114:117]
	v_mfma_f32_16x16x32_bf16 v[102:105], v[178:181], v[208:211], v[102:105]
	v_mfma_f32_16x16x32_bf16 v[98:101], v[186:189], v[208:211], v[98:101]
	v_mfma_f32_16x16x32_bf16 v[86:89], v[178:181], v[216:219], v[86:89]
	v_mfma_f32_16x16x32_bf16 v[82:85], v[186:189], v[216:219], v[82:85]
	v_mfma_f32_16x16x32_bf16 v[70:73], v[178:181], v[224:227], v[70:73]
	v_mfma_f32_16x16x32_bf16 v[66:69], v[186:189], v[224:227], v[66:69]
	v_mfma_f32_16x16x32_bf16 v[118:121], v[182:185], v[204:207], v[118:121]
	v_mfma_f32_16x16x32_bf16 v[114:117], v[190:193], v[204:207], v[114:117]
	v_mfma_f32_16x16x32_bf16 v[102:105], v[182:185], v[212:215], v[102:105]
	v_mfma_f32_16x16x32_bf16 v[98:101], v[190:193], v[212:215], v[98:101]
	v_mfma_f32_16x16x32_bf16 v[86:89], v[182:185], v[220:223], v[86:89]
	v_mfma_f32_16x16x32_bf16 v[82:85], v[190:193], v[220:223], v[82:85]
	v_mfma_f32_16x16x32_bf16 v[70:73], v[182:185], v[228:231], v[70:73]
	v_mfma_f32_16x16x32_bf16 v[66:69], v[190:193], v[228:231], v[66:69]
	s_barrier
	s_add_i32 s38, s70, s52
	s_add_i32 m0, s38, 0xffffff80
	ds_read_b128 v[200:203], v151 offset:49152
	ds_read_b128 v[204:207], v151 offset:50176
	ds_read_b128 v[208:211], v151 offset:51200
	ds_read_b128 v[212:215], v151 offset:52224
	ds_read_b128 v[216:219], v151 offset:53248
	ds_read_b128 v[220:223], v151 offset:54272
	ds_read_b128 v[224:227], v151 offset:55296
	ds_read_b128 v[228:231], v151 offset:56320
	global_load_lds_dwordx4 v158, s[36:37] offset:128
	s_add_i32 m0, s38, 0x1f80
	s_add_i32 s38, s71, s52
	global_load_lds_dwordx4 v134, s[36:37] offset:128
	s_add_u32 s36, s36, 0x80080
	s_addc_u32 s37, s37, 0
	s_mov_b32 m0, s38
	s_nop 0
	global_load_lds_dwordx4 v158, s[36:37]
	s_add_i32 m0, s38, 0x2000
	s_nop 0
	global_load_lds_dwordx4 v134, s[36:37]
	s_waitcnt vmcnt(6)
	s_waitcnt lgkmcnt(0)
	s_barrier
	v_mfma_f32_16x16x32_bf16 v[62:65], v[152:155], v[200:203], v[62:65]
	v_mfma_f32_16x16x32_bf16 v[58:61], v[170:173], v[200:203], v[58:61]
	v_mfma_f32_16x16x32_bf16 v[46:49], v[152:155], v[208:211], v[46:49]
	v_mfma_f32_16x16x32_bf16 v[42:45], v[170:173], v[208:211], v[42:45]
	v_mfma_f32_16x16x32_bf16 v[30:33], v[152:155], v[216:219], v[30:33]
	v_mfma_f32_16x16x32_bf16 v[26:29], v[170:173], v[216:219], v[26:29]
	v_mfma_f32_16x16x32_bf16 v[14:17], v[152:155], v[224:227], v[14:17]
	v_mfma_f32_16x16x32_bf16 v[10:13], v[170:173], v[224:227], v[10:13]
	v_mfma_f32_16x16x32_bf16 v[62:65], v[166:169], v[204:207], v[62:65]
	v_mfma_f32_16x16x32_bf16 v[58:61], v[174:177], v[204:207], v[58:61]
	v_mfma_f32_16x16x32_bf16 v[46:49], v[166:169], v[212:215], v[46:49]
	v_mfma_f32_16x16x32_bf16 v[42:45], v[174:177], v[212:215], v[42:45]
	v_mfma_f32_16x16x32_bf16 v[30:33], v[166:169], v[220:223], v[30:33]
	v_mfma_f32_16x16x32_bf16 v[26:29], v[174:177], v[220:223], v[26:29]
	v_mfma_f32_16x16x32_bf16 v[14:17], v[166:169], v[228:231], v[14:17]
	v_mfma_f32_16x16x32_bf16 v[10:13], v[174:177], v[228:231], v[10:13]
	v_mfma_f32_16x16x32_bf16 v[54:57], v[178:181], v[200:203], v[54:57]
	v_mfma_f32_16x16x32_bf16 v[50:53], v[186:189], v[200:203], v[50:53]
	v_mfma_f32_16x16x32_bf16 v[38:41], v[178:181], v[208:211], v[38:41]
	v_mfma_f32_16x16x32_bf16 v[34:37], v[186:189], v[208:211], v[34:37]
	v_mfma_f32_16x16x32_bf16 v[22:25], v[178:181], v[216:219], v[22:25]
	v_mfma_f32_16x16x32_bf16 v[18:21], v[186:189], v[216:219], v[18:21]
	v_mfma_f32_16x16x32_bf16 v[6:9], v[178:181], v[224:227], v[6:9]
	v_mfma_f32_16x16x32_bf16 v[2:5], v[186:189], v[224:227], v[2:5]
	v_mfma_f32_16x16x32_bf16 v[54:57], v[182:185], v[204:207], v[54:57]
	v_mfma_f32_16x16x32_bf16 v[50:53], v[190:193], v[204:207], v[50:53]
	v_mfma_f32_16x16x32_bf16 v[38:41], v[182:185], v[212:215], v[38:41]
	v_mfma_f32_16x16x32_bf16 v[34:37], v[190:193], v[212:215], v[34:37]
	v_mfma_f32_16x16x32_bf16 v[22:25], v[182:185], v[220:223], v[22:25]
	v_mfma_f32_16x16x32_bf16 v[18:21], v[190:193], v[220:223], v[18:21]
	v_mfma_f32_16x16x32_bf16 v[6:9], v[182:185], v[228:231], v[6:9]
	v_mfma_f32_16x16x32_bf16 v[2:5], v[190:193], v[228:231], v[2:5]
	s_barrier
	s_add_i32 s69, s69, 2
	s_add_u32 s30, s30, 0x100
	s_addc_u32 s31, s31, 0
	s_add_u32 s67, s67, 0x100
	s_addc_u32 s68, s68, 0
	s_cmp_gt_u32 s69, 29
	s_cbranch_scc0 .LBB0_139
	s_and_b64 vcc, exec, s[16:17]
	s_cbranch_vccz .LBB0_142
	s_barrier

; #define PG8_STAGE(bufoff, gbase, voff) do { _Pragma("unroll") for (int _i = 0; _i < 2; ++_i) \
;         __builtin_amdgcn_global_load_lds((const unsigned*)((const char*)(gbase) + (voff)[_i]), (PG8_LAS unsigned*)(lds + (bufoff) + ldsw + _i * 8192), 16, 0, 0); } while (0)
; #define PG8_LDA(dst, b, h) do { _Pragma("unroll") for (int m = 0; m < 4; ++m) _Pragma("unroll") for (int k = 0; k < 2; ++k) dst[m][k] = *(const PG8_LAS bf16x8*)(lds + PG8_SA(b, h) + aoff + m * 2048 + k * 1024); } while (0)
; #define PG8_LDB(dst, b, h) do { _Pragma("unroll") for (int n = 0; n < 2; ++n) _Pragma("unroll") for (int k = 0; k < 2; ++k) dst[n][k] = *(const PG8_LAS bf16x8*)(lds + PG8_SB(b, h) + boff + n * 2048 + k * 1024); } while (0)
; #define PG8_MMA(ai, bj, At, Bt) do { __builtin_amdgcn_s_setprio(1); _Pragma("unroll") for (int m = 0; m < 4; ++m) _Pragma("unroll") for (int n = 0; n < 2; ++n) _Pragma("unroll") for (int k = 0; k < 2; ++k) \
;         acc[ai][bj][m][n] = __builtin_amdgcn_mfma_f32_16x16x32_bf16(Bt[n][k], At[m][k], acc[ai][bj][m][n], 0, 0, 0); __builtin_amdgcn_s_setprio(0); } while (0)
; #define PG8_WAIT_V(n) asm volatile("s_waitcnt vmcnt(" #n ")" ::: "memory")
; #define PG8_WAIT_L(n) asm volatile("s_waitcnt lgkmcnt(" #n ")" ::: "memory")
; template <class Epi, class Sched, bool ALIGN_EPI = false, bool SP2 = false>
; __device__ __forceinline__ void gemm_phase(PG8_LAS unsigned char* lds, const Gemm g, const Sched& S, const Epi& E) {
;     ...
;             const bool last = (t == nt - 2);
;             const char* a1 = cA + (size_t)(t + 1) * kstep;
;             const char* a2 = last ? nA : cA + (size_t)(t + 2) * kstep; const char* b2 = last ? nB : cB + (size_t)(t + 2) * kstep;
;             const char* a3 = a2 + kstep; const char* b3 = b2 + kstep;
;             if (last && has_next) S.a_ready(nxt);
;             if constexpr (SP2) {
;             PG8_LDB(B0, 0, 0); PG8_LDB(B1, 0, 1); PG8_SCHED; PG8_LDA(At, 0, 0); PG8_STAGE(PG8_SA(1, 1), a1 + hstep, voffA);
;             PG8_WAIT_V(8); PG8_WAIT_L(0); PG8_BAR; PG8_MMA(0, 0, At, B0); PG8_MMA(0, 1, At, B1); PG8_BAR; PG8_SCHED;
;             PG8_LDA(At, 0, 1); PG8_STAGE(PG8_SB(0, 0), b2, voffB); PG8_STAGE(PG8_SB(0, 1), b2 + hstep, voffB); PG8_STAGE(PG8_SA(0, 0), a2, voffA);
;             PG8_WAIT_V(8); PG8_WAIT_L(0); PG8_BAR; PG8_MMA(1, 0, At, B0); PG8_MMA(1, 1, At, B1); PG8_BAR; PG8_SCHED;
.LBB0_667:
	s_add_u32 s30, s0, 0xfff80080
	s_addc_u32 s31, s1, -1
	s_add_i32 s66, 0, 0x10000
	s_cmp_eq_u32 s63, 28
	s_cselect_b32 s37, s23, s31
	s_cselect_b32 s36, s59, s30
	s_cselect_b32 s31, s19, s62
	s_cselect_b32 s30, s60, s61
	s_add_i32 s68, 0, 0x14000
	ds_read_b128 v[130:133], v244
	ds_read_b128 v[134:137], v244 offset:1024
	ds_read_b128 v[138:141], v244 offset:2048
	ds_read_b128 v[142:145], v244 offset:3072
	ds_read_b128 v[146:149], v245
	ds_read_b128 v[150:153], v245 offset:1024
	ds_read_b128 v[154:157], v245 offset:2048
	ds_read_b128 v[162:165], v245 offset:3072
	s_add_u32 s98, s0, 0xfff80000
	s_addc_u32 s99, s1, -1
	s_mov_b32 m0, s54
	s_nop 0
	global_load_lds_dwordx4 v172, s[98:99]
	s_mov_b32 m0, s55
	s_nop 0
	global_load_lds_dwordx4 v174, s[98:99]
	s_add_i32 m0, s48, 0xc000
	ds_read_b128 v[176:179], v201
	ds_read_b128 v[180:183], v201 offset:1024
	ds_read_b128 v[184:187], v201 offset:2048
	ds_read_b128 v[188:191], v201 offset:3072
	ds_read_b128 v[202:205], v201 offset:4096
	ds_read_b128 v[206:209], v201 offset:5120
	ds_read_b128 v[210:213], v201 offset:6144
	ds_read_b128 v[214:217], v201 offset:7168
	global_load_lds_dwordx4 v172, s[0:1]
	s_add_i32 m0, s48, 0xe000
	s_nop 0
	global_load_lds_dwordx4 v174, s[0:1]
	s_waitcnt vmcnt(8)
	s_waitcnt lgkmcnt(0)
	s_barrier
	v_mfma_f32_16x16x32_bf16 v[126:129], v[130:133], v[176:179], v[126:129]
	v_mfma_f32_16x16x32_bf16 v[122:125], v[138:141], v[176:179], v[122:125]
	v_mfma_f32_16x16x32_bf16 v[110:113], v[130:133], v[184:187], v[110:113]
	v_mfma_f32_16x16x32_bf16 v[106:109], v[138:141], v[184:187], v[106:109]
	v_mfma_f32_16x16x32_bf16 v[94:97], v[130:133], v[202:205], v[94:97]
	v_mfma_f32_16x16x32_bf16 v[90:93], v[138:141], v[202:205], v[90:93]
	v_mfma_f32_16x16x32_bf16 v[78:81], v[130:133], v[210:213], v[78:81]
	v_mfma_f32_16x16x32_bf16 v[74:77], v[138:141], v[210:213], v[74:77]
	v_mfma_f32_16x16x32_bf16 v[126:129], v[134:137], v[180:183], v[126:129]
	v_mfma_f32_16x16x32_bf16 v[122:125], v[142:145], v[180:183], v[122:125]
	v_mfma_f32_16x16x32_bf16 v[110:113], v[134:137], v[188:191], v[110:113]
	v_mfma_f32_16x16x32_bf16 v[106:109], v[142:145], v[188:191], v[106:109]
	v_mfma_f32_16x16x32_bf16 v[94:97], v[134:137], v[206:209], v[94:97]
	v_mfma_f32_16x16x32_bf16 v[90:93], v[142:145], v[206:209], v[90:93]
	v_mfma_f32_16x16x32_bf16 v[78:81], v[134:137], v[214:217], v[78:81]
	v_mfma_f32_16x16x32_bf16 v[74:77], v[142:145], v[214:217], v[74:77]
	v_mfma_f32_16x16x32_bf16 v[118:121], v[146:149], v[176:179], v[118:121]
	v_mfma_f32_16x16x32_bf16 v[114:117], v[154:157], v[176:179], v[114:117]
	v_mfma_f32_16x16x32_bf16 v[102:105], v[146:149], v[184:187], v[102:105]
	v_mfma_f32_16x16x32_bf16 v[98:101], v[154:157], v[184:187], v[98:101]
	v_mfma_f32_16x16x32_bf16 v[86:89], v[146:149], v[202:205], v[86:89]
	v_mfma_f32_16x16x32_bf16 v[82:85], v[154:157], v[202:205], v[82:85]
	v_mfma_f32_16x16x32_bf16 v[70:73], v[146:149], v[210:213], v[70:73]
	v_mfma_f32_16x16x32_bf16 v[66:69], v[154:157], v[210:213], v[66:69]
	v_mfma_f32_16x16x32_bf16 v[118:121], v[150:153], v[180:183], v[118:121]
	v_mfma_f32_16x16x32_bf16 v[114:117], v[162:165], v[180:183], v[114:117]
	v_mfma_f32_16x16x32_bf16 v[102:105], v[150:153], v[188:191], v[102:105]
	v_mfma_f32_16x16x32_bf16 v[98:101], v[162:165], v[188:191], v[98:101]
	v_mfma_f32_16x16x32_bf16 v[86:89], v[150:153], v[206:209], v[86:89]
	v_mfma_f32_16x16x32_bf16 v[82:85], v[162:165], v[206:209], v[82:85]
	v_mfma_f32_16x16x32_bf16 v[70:73], v[150:153], v[214:217], v[70:73]
	v_mfma_f32_16x16x32_bf16 v[66:69], v[162:165], v[214:217], v[66:69]
	s_barrier
	s_add_i32 s66, s66, s47
	s_mov_b32 m0, s66
	ds_read_b128 v[176:179], v201 offset:16384
	ds_read_b128 v[180:183], v201 offset:17408
	ds_read_b128 v[184:187], v201 offset:18432
	ds_read_b128 v[188:191], v201 offset:19456
	ds_read_b128 v[202:205], v201 offset:20480
	ds_read_b128 v[206:209], v201 offset:21504
	ds_read_b128 v[210:213], v201 offset:22528
	ds_read_b128 v[214:217], v201 offset:23552
	global_load_lds_dwordx4 v158, s[30:31]
	s_add_i32 m0, s66, 0x2000
	s_add_u32 s66, s30, 0x80000
	s_addc_u32 s67, s31, 0
	s_add_i32 s68, s68, s47
	global_load_lds_dwordx4 v166, s[30:31]
	s_mov_b32 m0, s68
	s_nop 0
	global_load_lds_dwordx4 v158, s[66:67]
	s_add_i32 m0, s68, 0x2000
	s_nop 0
	global_load_lds_dwordx4 v166, s[66:67]
	s_waitcnt vmcnt(6)
	s_waitcnt lgkmcnt(0)
	s_barrier
	v_mfma_f32_16x16x32_bf16 v[62:65], v[130:133], v[176:179], v[62:65]
	v_mfma_f32_16x16x32_bf16 v[58:61], v[138:141], v[176:179], v[58:61]
	v_mfma_f32_16x16x32_bf16 v[46:49], v[130:133], v[184:187], v[46:49]
	v_mfma_f32_16x16x32_bf16 v[42:45], v[138:141], v[184:187], v[42:45]
	v_mfma_f32_16x16x32_bf16 v[30:33], v[130:133], v[202:205], v[30:33]
	v_mfma_f32_16x16x32_bf16 v[26:29], v[138:141], v[202:205], v[26:29]
	v_mfma_f32_16x16x32_bf16 v[14:17], v[130:133], v[210:213], v[14:17]
	v_mfma_f32_16x16x32_bf16 v[10:13], v[138:141], v[210:213], v[10:13]
	v_mfma_f32_16x16x32_bf16 v[62:65], v[134:137], v[180:183], v[62:65]
	v_mfma_f32_16x16x32_bf16 v[58:61], v[142:145], v[180:183], v[58:61]
	v_mfma_f32_16x16x32_bf16 v[46:49], v[134:137], v[188:191], v[46:49]
	v_mfma_f32_16x16x32_bf16 v[42:45], v[142:145], v[188:191], v[42:45]
	v_mfma_f32_16x16x32_bf16 v[30:33], v[134:137], v[206:209], v[30:33]
	v_mfma_f32_16x16x32_bf16 v[26:29], v[142:145], v[206:209], v[26:29]
	v_mfma_f32_16x16x32_bf16 v[14:17], v[134:137], v[214:217], v[14:17]
	v_mfma_f32_16x16x32_bf16 v[10:13], v[142:145], v[214:217], v[10:13]
	v_mfma_f32_16x16x32_bf16 v[54:57], v[146:149], v[176:179], v[54:57]
	v_mfma_f32_16x16x32_bf16 v[50:53], v[154:157], v[176:179], v[50:53]
	v_mfma_f32_16x16x32_bf16 v[38:41], v[146:149], v[184:187], v[38:41]
	v_mfma_f32_16x16x32_bf16 v[34:37], v[154:157], v[184:187], v[34:37]
	v_mfma_f32_16x16x32_bf16 v[22:25], v[146:149], v[202:205], v[22:25]
	v_mfma_f32_16x16x32_bf16 v[18:21], v[154:157], v[202:205], v[18:21]
	v_mfma_f32_16x16x32_bf16 v[6:9], v[146:149], v[210:213], v[6:9]
	v_mfma_f32_16x16x32_bf16 v[2:5], v[154:157], v[210:213], v[2:5]
	v_mfma_f32_16x16x32_bf16 v[54:57], v[150:153], v[180:183], v[54:57]
	v_mfma_f32_16x16x32_bf16 v[50:53], v[162:165], v[180:183], v[50:53]
	v_mfma_f32_16x16x32_bf16 v[38:41], v[150:153], v[188:191], v[38:41]
	v_mfma_f32_16x16x32_bf16 v[34:37], v[162:165], v[188:191], v[34:37]
	v_mfma_f32_16x16x32_bf16 v[22:25], v[150:153], v[206:209], v[22:25]
	v_mfma_f32_16x16x32_bf16 v[18:21], v[162:165], v[206:209], v[18:21]
	v_mfma_f32_16x16x32_bf16 v[6:9], v[150:153], v[214:217], v[6:9]
	v_mfma_f32_16x16x32_bf16 v[2:5], v[162:165], v[214:217], v[2:5]
	s_barrier
; #define PG8_STAGE(bufoff, gbase, voff) do { _Pragma("unroll") for (int _i = 0; _i < 2; ++_i) \
;         __builtin_amdgcn_global_load_lds((const unsigned*)((const char*)(gbase) + (voff)[_i]), (PG8_LAS unsigned*)(lds + (bufoff) + ldsw + _i * 8192), 16, 0, 0); } while (0)
; #define PG8_LDA(dst, b, h) do { _Pragma("unroll") for (int m = 0; m < 4; ++m) _Pragma("unroll") for (int k = 0; k < 2; ++k) dst[m][k] = *(const PG8_LAS bf16x8*)(lds + PG8_SA(b, h) + aoff + m * 2048 + k * 1024); } while (0)
; #define PG8_LDB(dst, b, h) do { _Pragma("unroll") for (int n = 0; n < 2; ++n) _Pragma("unroll") for (int k = 0; k < 2; ++k) dst[n][k] = *(const PG8_LAS bf16x8*)(lds + PG8_SB(b, h) + boff + n * 2048 + k * 1024); } while (0)
; #define PG8_MMA(ai, bj, At, Bt) do { __builtin_amdgcn_s_setprio(1); _Pragma("unroll") for (int m = 0; m < 4; ++m) _Pragma("unroll") for (int n = 0; n < 2; ++n) _Pragma("unroll") for (int k = 0; k < 2; ++k) \
;         acc[ai][bj][m][n] = __builtin_amdgcn_mfma_f32_16x16x32_bf16(Bt[n][k], At[m][k], acc[ai][bj][m][n], 0, 0, 0); __builtin_amdgcn_s_setprio(0); } while (0)
; #define PG8_WAIT_V(n) asm volatile("s_waitcnt vmcnt(" #n ")" ::: "memory")
; #define PG8_WAIT_L(n) asm volatile("s_waitcnt lgkmcnt(" #n ")" ::: "memory")
; #define PG8_BAR __builtin_amdgcn_s_barrier()
; #define PG8_SCHED __builtin_amdgcn_sched_barrier(0)
; template <class Epi, class Sched, bool ALIGN_EPI = false, bool SP2 = false>
; __device__ __forceinline__ void gemm_phase(PG8_LAS unsigned char* lds, const Gemm g, const Sched& S, const Epi& E) {
;     ...
;             PG8_LDB(B0, 1, 0); PG8_LDB(B1, 1, 1); PG8_SCHED; PG8_LDA(At, 1, 0); PG8_STAGE(PG8_SA(0, 1), a2 + hstep, voffA);
;             PG8_WAIT_V(8); PG8_WAIT_L(0); PG8_BAR; PG8_MMA(0, 0, At, B0); PG8_MMA(0, 1, At, B1); PG8_BAR; PG8_SCHED;
;             PG8_LDA(At, 1, 1); PG8_STAGE(PG8_SB(1, 0), b3, voffB); PG8_STAGE(PG8_SB(1, 1), b3 + hstep, voffB); PG8_STAGE(PG8_SA(1, 0), a3, voffA);
;             PG8_WAIT_V(8); PG8_WAIT_L(0); PG8_BAR; PG8_MMA(1, 0, At, B0); PG8_MMA(1, 1, At, B1); PG8_BAR; PG8_SCHED;
	s_add_i32 s66, 0, 0x18000
	s_add_i32 s67, 0, 0x1c000
	ds_read_b128 v[130:133], v246
	ds_read_b128 v[134:137], v246 offset:1024
	ds_read_b128 v[138:141], v246 offset:2048
	ds_read_b128 v[142:145], v246 offset:3072
	ds_read_b128 v[146:149], v247
	ds_read_b128 v[150:153], v247 offset:1024
	ds_read_b128 v[154:157], v247 offset:2048
	ds_read_b128 v[162:165], v247 offset:3072
	s_mov_b32 m0, s48
	s_nop 0
	global_load_lds_dwordx4 v170, s[36:37]
	s_mov_b32 m0, s49
	s_nop 0
	global_load_lds_dwordx4 v168, s[36:37]
	s_add_u32 s36, s36, 0x80000
	s_addc_u32 s37, s37, 0
	s_mov_b32 m0, s50
	ds_read_b128 v[176:179], v201 offset:32768
	ds_read_b128 v[180:183], v201 offset:33792
	ds_read_b128 v[184:187], v201 offset:34816
	ds_read_b128 v[188:191], v201 offset:35840
	ds_read_b128 v[202:205], v201 offset:36864
	ds_read_b128 v[206:209], v201 offset:37888
	ds_read_b128 v[210:213], v201 offset:38912
	ds_read_b128 v[214:217], v201 offset:39936
	global_load_lds_dwordx4 v170, s[36:37]
	s_mov_b32 m0, s51
	s_nop 0
	global_load_lds_dwordx4 v168, s[36:37]
	s_waitcnt vmcnt(8)
	s_waitcnt lgkmcnt(0)
	s_barrier
	v_mfma_f32_16x16x32_bf16 v[126:129], v[130:133], v[176:179], v[126:129]
	v_mfma_f32_16x16x32_bf16 v[122:125], v[138:141], v[176:179], v[122:125]
	v_mfma_f32_16x16x32_bf16 v[110:113], v[130:133], v[184:187], v[110:113]
	v_mfma_f32_16x16x32_bf16 v[106:109], v[138:141], v[184:187], v[106:109]
	v_mfma_f32_16x16x32_bf16 v[94:97], v[130:133], v[202:205], v[94:97]
	v_mfma_f32_16x16x32_bf16 v[90:93], v[138:141], v[202:205], v[90:93]
	v_mfma_f32_16x16x32_bf16 v[78:81], v[130:133], v[210:213], v[78:81]
	v_mfma_f32_16x16x32_bf16 v[74:77], v[138:141], v[210:213], v[74:77]
	v_mfma_f32_16x16x32_bf16 v[126:129], v[134:137], v[180:183], v[126:129]
	v_mfma_f32_16x16x32_bf16 v[122:125], v[142:145], v[180:183], v[122:125]
	v_mfma_f32_16x16x32_bf16 v[110:113], v[134:137], v[188:191], v[110:113]
	v_mfma_f32_16x16x32_bf16 v[106:109], v[142:145], v[188:191], v[106:109]
	v_mfma_f32_16x16x32_bf16 v[94:97], v[134:137], v[206:209], v[94:97]
	v_mfma_f32_16x16x32_bf16 v[90:93], v[142:145], v[206:209], v[90:93]
	v_mfma_f32_16x16x32_bf16 v[78:81], v[134:137], v[214:217], v[78:81]
	v_mfma_f32_16x16x32_bf16 v[74:77], v[142:145], v[214:217], v[74:77]
	v_mfma_f32_16x16x32_bf16 v[118:121], v[146:149], v[176:179], v[118:121]
	v_mfma_f32_16x16x32_bf16 v[114:117], v[154:157], v[176:179], v[114:117]
	v_mfma_f32_16x16x32_bf16 v[102:105], v[146:149], v[184:187], v[102:105]
	v_mfma_f32_16x16x32_bf16 v[98:101], v[154:157], v[184:187], v[98:101]
	v_mfma_f32_16x16x32_bf16 v[86:89], v[146:149], v[202:205], v[86:89]
	v_mfma_f32_16x16x32_bf16 v[82:85], v[154:157], v[202:205], v[82:85]
	v_mfma_f32_16x16x32_bf16 v[70:73], v[146:149], v[210:213], v[70:73]
	v_mfma_f32_16x16x32_bf16 v[66:69], v[154:157], v[210:213], v[66:69]
	v_mfma_f32_16x16x32_bf16 v[118:121], v[150:153], v[180:183], v[118:121]
	v_mfma_f32_16x16x32_bf16 v[114:117], v[162:165], v[180:183], v[114:117]
	v_mfma_f32_16x16x32_bf16 v[102:105], v[150:153], v[188:191], v[102:105]
	v_mfma_f32_16x16x32_bf16 v[98:101], v[162:165], v[188:191], v[98:101]
	v_mfma_f32_16x16x32_bf16 v[86:89], v[150:153], v[206:209], v[86:89]
	v_mfma_f32_16x16x32_bf16 v[82:85], v[162:165], v[206:209], v[82:85]
	v_mfma_f32_16x16x32_bf16 v[70:73], v[150:153], v[214:217], v[70:73]
	v_mfma_f32_16x16x32_bf16 v[66:69], v[162:165], v[214:217], v[66:69]
	s_barrier
	s_add_i32 s36, s66, s47
	s_add_i32 m0, s36, 0xffffff80
	ds_read_b128 v[176:179], v201 offset:49152
	ds_read_b128 v[180:183], v201 offset:50176
	ds_read_b128 v[184:187], v201 offset:51200
	ds_read_b128 v[188:191], v201 offset:52224
	ds_read_b128 v[202:205], v201 offset:53248
	ds_read_b128 v[206:209], v201 offset:54272
	ds_read_b128 v[210:213], v201 offset:55296
	ds_read_b128 v[214:217], v201 offset:56320
	global_load_lds_dwordx4 v158, s[30:31] offset:128
	s_add_i32 m0, s36, 0x1f80
	s_add_i32 s36, s67, s47
	global_load_lds_dwordx4 v166, s[30:31] offset:128
	s_add_u32 s30, s30, 0x80080
	s_addc_u32 s31, s31, 0
	s_mov_b32 m0, s36
	s_nop 0
	global_load_lds_dwordx4 v158, s[30:31]
	s_add_i32 m0, s36, 0x2000
	s_nop 0
	global_load_lds_dwordx4 v166, s[30:31]
	s_waitcnt vmcnt(6)
	s_waitcnt lgkmcnt(0)
	s_barrier
	v_mfma_f32_16x16x32_bf16 v[62:65], v[130:133], v[176:179], v[62:65]
	v_mfma_f32_16x16x32_bf16 v[58:61], v[138:141], v[176:179], v[58:61]
	v_mfma_f32_16x16x32_bf16 v[46:49], v[130:133], v[184:187], v[46:49]
	v_mfma_f32_16x16x32_bf16 v[42:45], v[138:141], v[184:187], v[42:45]
	v_mfma_f32_16x16x32_bf16 v[30:33], v[130:133], v[202:205], v[30:33]
	v_mfma_f32_16x16x32_bf16 v[26:29], v[138:141], v[202:205], v[26:29]
	v_mfma_f32_16x16x32_bf16 v[14:17], v[130:133], v[210:213], v[14:17]
	v_mfma_f32_16x16x32_bf16 v[10:13], v[138:141], v[210:213], v[10:13]
	v_mfma_f32_16x16x32_bf16 v[62:65], v[134:137], v[180:183], v[62:65]
	v_mfma_f32_16x16x32_bf16 v[58:61], v[142:145], v[180:183], v[58:61]
	v_mfma_f32_16x16x32_bf16 v[46:49], v[134:137], v[188:191], v[46:49]
	v_mfma_f32_16x16x32_bf16 v[42:45], v[142:145], v[188:191], v[42:45]
	v_mfma_f32_16x16x32_bf16 v[30:33], v[134:137], v[206:209], v[30:33]
	v_mfma_f32_16x16x32_bf16 v[26:29], v[142:145], v[206:209], v[26:29]
	v_mfma_f32_16x16x32_bf16 v[14:17], v[134:137], v[214:217], v[14:17]
	v_mfma_f32_16x16x32_bf16 v[10:13], v[142:145], v[214:217], v[10:13]
	v_mfma_f32_16x16x32_bf16 v[54:57], v[146:149], v[176:179], v[54:57]
	v_mfma_f32_16x16x32_bf16 v[50:53], v[154:157], v[176:179], v[50:53]
	v_mfma_f32_16x16x32_bf16 v[38:41], v[146:149], v[184:187], v[38:41]
	v_mfma_f32_16x16x32_bf16 v[34:37], v[154:157], v[184:187], v[34:37]
	v_mfma_f32_16x16x32_bf16 v[22:25], v[146:149], v[202:205], v[22:25]
	v_mfma_f32_16x16x32_bf16 v[18:21], v[154:157], v[202:205], v[18:21]
	v_mfma_f32_16x16x32_bf16 v[6:9], v[146:149], v[210:213], v[6:9]
	v_mfma_f32_16x16x32_bf16 v[2:5], v[154:157], v[210:213], v[2:5]
	v_mfma_f32_16x16x32_bf16 v[54:57], v[150:153], v[180:183], v[54:57]
	v_mfma_f32_16x16x32_bf16 v[50:53], v[162:165], v[180:183], v[50:53]
	v_mfma_f32_16x16x32_bf16 v[38:41], v[150:153], v[188:191], v[38:41]
	v_mfma_f32_16x16x32_bf16 v[34:37], v[162:165], v[188:191], v[34:37]
	v_mfma_f32_16x16x32_bf16 v[22:25], v[150:153], v[206:209], v[22:25]
	v_mfma_f32_16x16x32_bf16 v[18:21], v[162:165], v[206:209], v[18:21]
	v_mfma_f32_16x16x32_bf16 v[6:9], v[150:153], v[214:217], v[6:9]
	v_mfma_f32_16x16x32_bf16 v[2:5], v[162:165], v[214:217], v[2:5]
	s_barrier
	s_add_i32 s63, s63, 2
	s_add_u32 s0, s0, 0x100
	s_addc_u32 s1, s1, 0
	s_add_u32 s61, s61, 0x100
	s_addc_u32 s62, s62, 0
	s_cmp_gt_u32 s63, 29
	s_cbranch_scc0 .LBB0_667
	s_and_b64 vcc, exec, s[16:17]
	s_cbranch_vccz .LBB0_670
	s_barrier

; #define PG8_STAGE(bufoff, gbase, voff) do { _Pragma("unroll") for (int _i = 0; _i < 2; ++_i) \
;         __builtin_amdgcn_global_load_lds((const unsigned*)((const char*)(gbase) + (voff)[_i]), (PG8_LAS unsigned*)(lds + (bufoff) + ldsw + _i * 8192), 16, 0, 0); } while (0)
; #define PG8_LDA(dst, b, h) do { _Pragma("unroll") for (int m = 0; m < 4; ++m) _Pragma("unroll") for (int k = 0; k < 2; ++k) dst[m][k] = *(const PG8_LAS bf16x8*)(lds + PG8_SA(b, h) + aoff + m * 2048 + k * 1024); } while (0)
; #define PG8_LDB(dst, b, h) do { _Pragma("unroll") for (int n = 0; n < 2; ++n) _Pragma("unroll") for (int k = 0; k < 2; ++k) dst[n][k] = *(const PG8_LAS bf16x8*)(lds + PG8_SB(b, h) + boff + n * 2048 + k * 1024); } while (0)
; #define PG8_MMA(ai, bj, At, Bt) do { __builtin_amdgcn_s_setprio(1); _Pragma("unroll") for (int m = 0; m < 4; ++m) _Pragma("unroll") for (int n = 0; n < 2; ++n) _Pragma("unroll") for (int k = 0; k < 2; ++k) \
;         acc[ai][bj][m][n] = __builtin_amdgcn_mfma_f32_16x16x32_bf16(Bt[n][k], At[m][k], acc[ai][bj][m][n], 0, 0, 0); __builtin_amdgcn_s_setprio(0); } while (0)
; #define PG8_WAIT_V(n) asm volatile("s_waitcnt vmcnt(" #n ")" ::: "memory")
; #define PG8_WAIT_L(n) asm volatile("s_waitcnt lgkmcnt(" #n ")" ::: "memory")
; template <class Epi, class Sched, bool ALIGN_EPI = false, bool SP2 = false>
; __device__ __forceinline__ void gemm_phase(PG8_LAS unsigned char* lds, const Gemm g, const Sched& S, const Epi& E) {
;     ...
;             const bool last = (t == nt - 2);
;             const char* a1 = cA + (size_t)(t + 1) * kstep;
;             const char* a2 = last ? nA : cA + (size_t)(t + 2) * kstep; const char* b2 = last ? nB : cB + (size_t)(t + 2) * kstep;
;             const char* a3 = a2 + kstep; const char* b3 = b2 + kstep;
;             if (last && has_next) S.a_ready(nxt);
;             if constexpr (SP2) {
;             PG8_LDB(B0, 0, 0); PG8_LDB(B1, 0, 1); PG8_SCHED; PG8_LDA(At, 0, 0); PG8_STAGE(PG8_SA(1, 1), a1 + hstep, voffA);
;             PG8_WAIT_V(8); PG8_WAIT_L(0); PG8_BAR; PG8_MMA(0, 0, At, B0); PG8_MMA(0, 1, At, B1); PG8_BAR; PG8_SCHED;
;             PG8_LDA(At, 0, 1); PG8_STAGE(PG8_SB(0, 0), b2, voffB); PG8_STAGE(PG8_SB(0, 1), b2 + hstep, voffB); PG8_STAGE(PG8_SA(0, 0), a2, voffA);
;             PG8_WAIT_V(8); PG8_WAIT_L(0); PG8_BAR; PG8_MMA(1, 0, At, B0); PG8_MMA(1, 1, At, B1); PG8_BAR; PG8_SCHED;
.LBB0_762:
	s_add_u32 s30, s0, 0xfff80080
	s_addc_u32 s31, s1, -1
	s_add_i32 s67, 0, 0x10000
	s_cmp_eq_u32 s66, 28
	s_cselect_b32 s37, s23, s31
	s_cselect_b32 s36, s60, s30
	s_cselect_b32 s31, s19, s63
	s_cselect_b32 s30, s61, s62
	s_add_i32 s70, 0, 0x14000
	ds_read_b128 v[140:143], v244
	ds_read_b128 v[152:155], v244 offset:1024
	ds_read_b128 v[162:165], v244 offset:2048
	ds_read_b128 v[166:169], v244 offset:3072
	ds_read_b128 v[170:173], v245
	ds_read_b128 v[174:177], v245 offset:1024
	ds_read_b128 v[178:181], v245 offset:2048
	ds_read_b128 v[182:185], v245 offset:3072
	s_add_u32 s98, s0, 0xfff80000
	s_addc_u32 s99, s1, -1
	s_mov_b32 m0, s52
	s_nop 0
	global_load_lds_dwordx4 v136, s[98:99]
	s_mov_b32 m0, s53
	s_nop 0
	global_load_lds_dwordx4 v138, s[98:99]
	s_add_i32 m0, s47, 0xc000
	ds_read_b128 v[186:189], v150
	ds_read_b128 v[190:193], v150 offset:1024
	ds_read_b128 v[200:203], v150 offset:2048
	ds_read_b128 v[204:207], v150 offset:3072
	ds_read_b128 v[208:211], v150 offset:4096
	ds_read_b128 v[212:215], v150 offset:5120
	ds_read_b128 v[216:219], v150 offset:6144
	ds_read_b128 v[220:223], v150 offset:7168
	global_load_lds_dwordx4 v136, s[0:1]
	s_add_i32 m0, s47, 0xe000
	s_nop 0
	global_load_lds_dwordx4 v138, s[0:1]
	s_waitcnt vmcnt(8)
	s_waitcnt lgkmcnt(0)
	s_barrier
	v_mfma_f32_16x16x32_bf16 v[126:129], v[140:143], v[186:189], v[126:129]
	v_mfma_f32_16x16x32_bf16 v[122:125], v[162:165], v[186:189], v[122:125]
	v_mfma_f32_16x16x32_bf16 v[110:113], v[140:143], v[200:203], v[110:113]
	v_mfma_f32_16x16x32_bf16 v[106:109], v[162:165], v[200:203], v[106:109]
	v_mfma_f32_16x16x32_bf16 v[94:97], v[140:143], v[208:211], v[94:97]
	v_mfma_f32_16x16x32_bf16 v[90:93], v[162:165], v[208:211], v[90:93]
	v_mfma_f32_16x16x32_bf16 v[78:81], v[140:143], v[216:219], v[78:81]
	v_mfma_f32_16x16x32_bf16 v[74:77], v[162:165], v[216:219], v[74:77]
	v_mfma_f32_16x16x32_bf16 v[126:129], v[152:155], v[190:193], v[126:129]
	v_mfma_f32_16x16x32_bf16 v[122:125], v[166:169], v[190:193], v[122:125]
	v_mfma_f32_16x16x32_bf16 v[110:113], v[152:155], v[204:207], v[110:113]
	v_mfma_f32_16x16x32_bf16 v[106:109], v[166:169], v[204:207], v[106:109]
	v_mfma_f32_16x16x32_bf16 v[94:97], v[152:155], v[212:215], v[94:97]
	v_mfma_f32_16x16x32_bf16 v[90:93], v[166:169], v[212:215], v[90:93]
	v_mfma_f32_16x16x32_bf16 v[78:81], v[152:155], v[220:223], v[78:81]
	v_mfma_f32_16x16x32_bf16 v[74:77], v[166:169], v[220:223], v[74:77]
	v_mfma_f32_16x16x32_bf16 v[118:121], v[170:173], v[186:189], v[118:121]
	v_mfma_f32_16x16x32_bf16 v[114:117], v[178:181], v[186:189], v[114:117]
	v_mfma_f32_16x16x32_bf16 v[102:105], v[170:173], v[200:203], v[102:105]
	v_mfma_f32_16x16x32_bf16 v[98:101], v[178:181], v[200:203], v[98:101]
	v_mfma_f32_16x16x32_bf16 v[86:89], v[170:173], v[208:211], v[86:89]
	v_mfma_f32_16x16x32_bf16 v[82:85], v[178:181], v[208:211], v[82:85]
	v_mfma_f32_16x16x32_bf16 v[70:73], v[170:173], v[216:219], v[70:73]
	v_mfma_f32_16x16x32_bf16 v[66:69], v[178:181], v[216:219], v[66:69]
	v_mfma_f32_16x16x32_bf16 v[118:121], v[174:177], v[190:193], v[118:121]
	v_mfma_f32_16x16x32_bf16 v[114:117], v[182:185], v[190:193], v[114:117]
	v_mfma_f32_16x16x32_bf16 v[102:105], v[174:177], v[204:207], v[102:105]
	v_mfma_f32_16x16x32_bf16 v[98:101], v[182:185], v[204:207], v[98:101]
	v_mfma_f32_16x16x32_bf16 v[86:89], v[174:177], v[212:215], v[86:89]
	v_mfma_f32_16x16x32_bf16 v[82:85], v[182:185], v[212:215], v[82:85]
	v_mfma_f32_16x16x32_bf16 v[70:73], v[174:177], v[220:223], v[70:73]
	v_mfma_f32_16x16x32_bf16 v[66:69], v[182:185], v[220:223], v[66:69]
	s_barrier
	s_add_i32 s67, s67, s46
	s_mov_b32 m0, s67
	ds_read_b128 v[186:189], v150 offset:16384
	ds_read_b128 v[190:193], v150 offset:17408
	ds_read_b128 v[200:203], v150 offset:18432
	ds_read_b128 v[204:207], v150 offset:19456
	ds_read_b128 v[208:211], v150 offset:20480
	ds_read_b128 v[212:215], v150 offset:21504
	ds_read_b128 v[216:219], v150 offset:22528
	ds_read_b128 v[220:223], v150 offset:23552
	global_load_lds_dwordx4 v158, s[30:31]
	s_add_i32 m0, s67, 0x2000
	s_add_u32 s68, s30, 0x80000
	s_addc_u32 s69, s31, 0
	s_add_i32 s67, s70, s46
	global_load_lds_dwordx4 v134, s[30:31]
	s_mov_b32 m0, s67
	s_nop 0
	global_load_lds_dwordx4 v158, s[68:69]
	s_add_i32 m0, s67, 0x2000
	s_nop 0
	global_load_lds_dwordx4 v134, s[68:69]
	s_waitcnt vmcnt(6)
	s_waitcnt lgkmcnt(0)
	s_barrier
	v_mfma_f32_16x16x32_bf16 v[62:65], v[140:143], v[186:189], v[62:65]
	v_mfma_f32_16x16x32_bf16 v[58:61], v[162:165], v[186:189], v[58:61]
	v_mfma_f32_16x16x32_bf16 v[46:49], v[140:143], v[200:203], v[46:49]
	v_mfma_f32_16x16x32_bf16 v[42:45], v[162:165], v[200:203], v[42:45]
	v_mfma_f32_16x16x32_bf16 v[30:33], v[140:143], v[208:211], v[30:33]
	v_mfma_f32_16x16x32_bf16 v[26:29], v[162:165], v[208:211], v[26:29]
	v_mfma_f32_16x16x32_bf16 v[14:17], v[140:143], v[216:219], v[14:17]
	v_mfma_f32_16x16x32_bf16 v[10:13], v[162:165], v[216:219], v[10:13]
	v_mfma_f32_16x16x32_bf16 v[62:65], v[152:155], v[190:193], v[62:65]
	v_mfma_f32_16x16x32_bf16 v[58:61], v[166:169], v[190:193], v[58:61]
	v_mfma_f32_16x16x32_bf16 v[46:49], v[152:155], v[204:207], v[46:49]
	v_mfma_f32_16x16x32_bf16 v[42:45], v[166:169], v[204:207], v[42:45]
	v_mfma_f32_16x16x32_bf16 v[30:33], v[152:155], v[212:215], v[30:33]
	v_mfma_f32_16x16x32_bf16 v[26:29], v[166:169], v[212:215], v[26:29]
	v_mfma_f32_16x16x32_bf16 v[14:17], v[152:155], v[220:223], v[14:17]
	v_mfma_f32_16x16x32_bf16 v[10:13], v[166:169], v[220:223], v[10:13]
	v_mfma_f32_16x16x32_bf16 v[54:57], v[170:173], v[186:189], v[54:57]
	v_mfma_f32_16x16x32_bf16 v[50:53], v[178:181], v[186:189], v[50:53]
	v_mfma_f32_16x16x32_bf16 v[38:41], v[170:173], v[200:203], v[38:41]
	v_mfma_f32_16x16x32_bf16 v[34:37], v[178:181], v[200:203], v[34:37]
	v_mfma_f32_16x16x32_bf16 v[22:25], v[170:173], v[208:211], v[22:25]
	v_mfma_f32_16x16x32_bf16 v[18:21], v[178:181], v[208:211], v[18:21]
	v_mfma_f32_16x16x32_bf16 v[6:9], v[170:173], v[216:219], v[6:9]
	v_mfma_f32_16x16x32_bf16 v[2:5], v[178:181], v[216:219], v[2:5]
	v_mfma_f32_16x16x32_bf16 v[54:57], v[174:177], v[190:193], v[54:57]
	v_mfma_f32_16x16x32_bf16 v[50:53], v[182:185], v[190:193], v[50:53]
	v_mfma_f32_16x16x32_bf16 v[38:41], v[174:177], v[204:207], v[38:41]
	v_mfma_f32_16x16x32_bf16 v[34:37], v[182:185], v[204:207], v[34:37]
	v_mfma_f32_16x16x32_bf16 v[22:25], v[174:177], v[212:215], v[22:25]
	v_mfma_f32_16x16x32_bf16 v[18:21], v[182:185], v[212:215], v[18:21]
	v_mfma_f32_16x16x32_bf16 v[6:9], v[174:177], v[220:223], v[6:9]
	v_mfma_f32_16x16x32_bf16 v[2:5], v[182:185], v[220:223], v[2:5]
	s_barrier
; #define PG8_STAGE(bufoff, gbase, voff) do { _Pragma("unroll") for (int _i = 0; _i < 2; ++_i) \
;         __builtin_amdgcn_global_load_lds((const unsigned*)((const char*)(gbase) + (voff)[_i]), (PG8_LAS unsigned*)(lds + (bufoff) + ldsw + _i * 8192), 16, 0, 0); } while (0)
; #define PG8_LDA(dst, b, h) do { _Pragma("unroll") for (int m = 0; m < 4; ++m) _Pragma("unroll") for (int k = 0; k < 2; ++k) dst[m][k] = *(const PG8_LAS bf16x8*)(lds + PG8_SA(b, h) + aoff + m * 2048 + k * 1024); } while (0)
; #define PG8_LDB(dst, b, h) do { _Pragma("unroll") for (int n = 0; n < 2; ++n) _Pragma("unroll") for (int k = 0; k < 2; ++k) dst[n][k] = *(const PG8_LAS bf16x8*)(lds + PG8_SB(b, h) + boff + n * 2048 + k * 1024); } while (0)
; #define PG8_MMA(ai, bj, At, Bt) do { __builtin_amdgcn_s_setprio(1); _Pragma("unroll") for (int m = 0; m < 4; ++m) _Pragma("unroll") for (int n = 0; n < 2; ++n) _Pragma("unroll") for (int k = 0; k < 2; ++k) \
;         acc[ai][bj][m][n] = __builtin_amdgcn_mfma_f32_16x16x32_bf16(Bt[n][k], At[m][k], acc[ai][bj][m][n], 0, 0, 0); __builtin_amdgcn_s_setprio(0); } while (0)
; #define PG8_WAIT_V(n) asm volatile("s_waitcnt vmcnt(" #n ")" ::: "memory")
; #define PG8_WAIT_L(n) asm volatile("s_waitcnt lgkmcnt(" #n ")" ::: "memory")
; #define PG8_BAR __builtin_amdgcn_s_barrier()
; #define PG8_SCHED __builtin_amdgcn_sched_barrier(0)
; template <class Epi, class Sched, bool ALIGN_EPI = false, bool SP2 = false>
; __device__ __forceinline__ void gemm_phase(PG8_LAS unsigned char* lds, const Gemm g, const Sched& S, const Epi& E) {
;     ...
;             PG8_LDB(B0, 1, 0); PG8_LDB(B1, 1, 1); PG8_SCHED; PG8_LDA(At, 1, 0); PG8_STAGE(PG8_SA(0, 1), a2 + hstep, voffA);
;             PG8_WAIT_V(8); PG8_WAIT_L(0); PG8_BAR; PG8_MMA(0, 0, At, B0); PG8_MMA(0, 1, At, B1); PG8_BAR; PG8_SCHED;
;             PG8_LDA(At, 1, 1); PG8_STAGE(PG8_SB(1, 0), b3, voffB); PG8_STAGE(PG8_SB(1, 1), b3 + hstep, voffB); PG8_STAGE(PG8_SA(1, 0), a3, voffA);
;             PG8_WAIT_V(8); PG8_WAIT_L(0); PG8_BAR; PG8_MMA(1, 0, At, B0); PG8_MMA(1, 1, At, B1); PG8_BAR; PG8_SCHED;
	s_add_i32 s67, 0, 0x18000
	s_add_i32 s68, 0, 0x1c000
	ds_read_b128 v[140:143], v246
	ds_read_b128 v[152:155], v246 offset:1024
	ds_read_b128 v[162:165], v246 offset:2048
	ds_read_b128 v[166:169], v246 offset:3072
	ds_read_b128 v[170:173], v247
	ds_read_b128 v[174:177], v247 offset:1024
	ds_read_b128 v[178:181], v247 offset:2048
	ds_read_b128 v[182:185], v247 offset:3072
	s_mov_b32 m0, s47
	s_nop 0
	global_load_lds_dwordx4 v130, s[36:37]
	s_mov_b32 m0, s48
	s_nop 0
	global_load_lds_dwordx4 v132, s[36:37]
	s_add_u32 s36, s36, 0x80000
	s_addc_u32 s37, s37, 0
	s_mov_b32 m0, s49
	ds_read_b128 v[186:189], v150 offset:32768
	ds_read_b128 v[190:193], v150 offset:33792
	ds_read_b128 v[200:203], v150 offset:34816
	ds_read_b128 v[204:207], v150 offset:35840
	ds_read_b128 v[208:211], v150 offset:36864
	ds_read_b128 v[212:215], v150 offset:37888
	ds_read_b128 v[216:219], v150 offset:38912
	ds_read_b128 v[220:223], v150 offset:39936
	global_load_lds_dwordx4 v130, s[36:37]
	s_mov_b32 m0, s50
	s_nop 0
	global_load_lds_dwordx4 v132, s[36:37]
	s_waitcnt vmcnt(8)
	s_waitcnt lgkmcnt(0)
	s_barrier
	v_mfma_f32_16x16x32_bf16 v[126:129], v[140:143], v[186:189], v[126:129]
	v_mfma_f32_16x16x32_bf16 v[122:125], v[162:165], v[186:189], v[122:125]
	v_mfma_f32_16x16x32_bf16 v[110:113], v[140:143], v[200:203], v[110:113]
	v_mfma_f32_16x16x32_bf16 v[106:109], v[162:165], v[200:203], v[106:109]
	v_mfma_f32_16x16x32_bf16 v[94:97], v[140:143], v[208:211], v[94:97]
	v_mfma_f32_16x16x32_bf16 v[90:93], v[162:165], v[208:211], v[90:93]
	v_mfma_f32_16x16x32_bf16 v[78:81], v[140:143], v[216:219], v[78:81]
	v_mfma_f32_16x16x32_bf16 v[74:77], v[162:165], v[216:219], v[74:77]
	v_mfma_f32_16x16x32_bf16 v[126:129], v[152:155], v[190:193], v[126:129]
	v_mfma_f32_16x16x32_bf16 v[122:125], v[166:169], v[190:193], v[122:125]
	v_mfma_f32_16x16x32_bf16 v[110:113], v[152:155], v[204:207], v[110:113]
	v_mfma_f32_16x16x32_bf16 v[106:109], v[166:169], v[204:207], v[106:109]
	v_mfma_f32_16x16x32_bf16 v[94:97], v[152:155], v[212:215], v[94:97]
	v_mfma_f32_16x16x32_bf16 v[90:93], v[166:169], v[212:215], v[90:93]
	v_mfma_f32_16x16x32_bf16 v[78:81], v[152:155], v[220:223], v[78:81]
	v_mfma_f32_16x16x32_bf16 v[74:77], v[166:169], v[220:223], v[74:77]
	v_mfma_f32_16x16x32_bf16 v[118:121], v[170:173], v[186:189], v[118:121]
	v_mfma_f32_16x16x32_bf16 v[114:117], v[178:181], v[186:189], v[114:117]
	v_mfma_f32_16x16x32_bf16 v[102:105], v[170:173], v[200:203], v[102:105]
	v_mfma_f32_16x16x32_bf16 v[98:101], v[178:181], v[200:203], v[98:101]
	v_mfma_f32_16x16x32_bf16 v[86:89], v[170:173], v[208:211], v[86:89]
	v_mfma_f32_16x16x32_bf16 v[82:85], v[178:181], v[208:211], v[82:85]
	v_mfma_f32_16x16x32_bf16 v[70:73], v[170:173], v[216:219], v[70:73]
	v_mfma_f32_16x16x32_bf16 v[66:69], v[178:181], v[216:219], v[66:69]
	v_mfma_f32_16x16x32_bf16 v[118:121], v[174:177], v[190:193], v[118:121]
	v_mfma_f32_16x16x32_bf16 v[114:117], v[182:185], v[190:193], v[114:117]
	v_mfma_f32_16x16x32_bf16 v[102:105], v[174:177], v[204:207], v[102:105]
	v_mfma_f32_16x16x32_bf16 v[98:101], v[182:185], v[204:207], v[98:101]
	v_mfma_f32_16x16x32_bf16 v[86:89], v[174:177], v[212:215], v[86:89]
	v_mfma_f32_16x16x32_bf16 v[82:85], v[182:185], v[212:215], v[82:85]
	v_mfma_f32_16x16x32_bf16 v[70:73], v[174:177], v[220:223], v[70:73]
	v_mfma_f32_16x16x32_bf16 v[66:69], v[182:185], v[220:223], v[66:69]
	s_barrier
	s_add_i32 s36, s67, s46
	s_add_i32 m0, s36, 0xffffff80
	ds_read_b128 v[186:189], v150 offset:49152
	ds_read_b128 v[190:193], v150 offset:50176
	ds_read_b128 v[200:203], v150 offset:51200
	ds_read_b128 v[204:207], v150 offset:52224
	ds_read_b128 v[208:211], v150 offset:53248
	ds_read_b128 v[212:215], v150 offset:54272
	ds_read_b128 v[216:219], v150 offset:55296
	ds_read_b128 v[220:223], v150 offset:56320
	global_load_lds_dwordx4 v158, s[30:31] offset:128
	s_add_i32 m0, s36, 0x1f80
	s_add_i32 s36, s68, s46
	global_load_lds_dwordx4 v134, s[30:31] offset:128
	s_add_u32 s30, s30, 0x80080
	s_addc_u32 s31, s31, 0
	s_mov_b32 m0, s36
	s_nop 0
	global_load_lds_dwordx4 v158, s[30:31]
	s_add_i32 m0, s36, 0x2000
	s_nop 0
	global_load_lds_dwordx4 v134, s[30:31]
	s_waitcnt vmcnt(6)
	s_waitcnt lgkmcnt(0)
	s_barrier
	v_mfma_f32_16x16x32_bf16 v[62:65], v[140:143], v[186:189], v[62:65]
	v_mfma_f32_16x16x32_bf16 v[58:61], v[162:165], v[186:189], v[58:61]
	v_mfma_f32_16x16x32_bf16 v[46:49], v[140:143], v[200:203], v[46:49]
	v_mfma_f32_16x16x32_bf16 v[42:45], v[162:165], v[200:203], v[42:45]
	v_mfma_f32_16x16x32_bf16 v[30:33], v[140:143], v[208:211], v[30:33]
	v_mfma_f32_16x16x32_bf16 v[26:29], v[162:165], v[208:211], v[26:29]
	v_mfma_f32_16x16x32_bf16 v[14:17], v[140:143], v[216:219], v[14:17]
	v_mfma_f32_16x16x32_bf16 v[10:13], v[162:165], v[216:219], v[10:13]
	v_mfma_f32_16x16x32_bf16 v[62:65], v[152:155], v[190:193], v[62:65]
	v_mfma_f32_16x16x32_bf16 v[58:61], v[166:169], v[190:193], v[58:61]
	v_mfma_f32_16x16x32_bf16 v[46:49], v[152:155], v[204:207], v[46:49]
	v_mfma_f32_16x16x32_bf16 v[42:45], v[166:169], v[204:207], v[42:45]
	v_mfma_f32_16x16x32_bf16 v[30:33], v[152:155], v[212:215], v[30:33]
	v_mfma_f32_16x16x32_bf16 v[26:29], v[166:169], v[212:215], v[26:29]
	v_mfma_f32_16x16x32_bf16 v[14:17], v[152:155], v[220:223], v[14:17]
	v_mfma_f32_16x16x32_bf16 v[10:13], v[166:169], v[220:223], v[10:13]
	v_mfma_f32_16x16x32_bf16 v[54:57], v[170:173], v[186:189], v[54:57]
	v_mfma_f32_16x16x32_bf16 v[50:53], v[178:181], v[186:189], v[50:53]
	v_mfma_f32_16x16x32_bf16 v[38:41], v[170:173], v[200:203], v[38:41]
	v_mfma_f32_16x16x32_bf16 v[34:37], v[178:181], v[200:203], v[34:37]
	v_mfma_f32_16x16x32_bf16 v[22:25], v[170:173], v[208:211], v[22:25]
	v_mfma_f32_16x16x32_bf16 v[18:21], v[178:181], v[208:211], v[18:21]
	v_mfma_f32_16x16x32_bf16 v[6:9], v[170:173], v[216:219], v[6:9]
	v_mfma_f32_16x16x32_bf16 v[2:5], v[178:181], v[216:219], v[2:5]
	v_mfma_f32_16x16x32_bf16 v[54:57], v[174:177], v[190:193], v[54:57]
	v_mfma_f32_16x16x32_bf16 v[50:53], v[182:185], v[190:193], v[50:53]
	v_mfma_f32_16x16x32_bf16 v[38:41], v[174:177], v[204:207], v[38:41]
	v_mfma_f32_16x16x32_bf16 v[34:37], v[182:185], v[204:207], v[34:37]
	v_mfma_f32_16x16x32_bf16 v[22:25], v[174:177], v[212:215], v[22:25]
	v_mfma_f32_16x16x32_bf16 v[18:21], v[182:185], v[212:215], v[18:21]
	v_mfma_f32_16x16x32_bf16 v[6:9], v[174:177], v[220:223], v[6:9]
	v_mfma_f32_16x16x32_bf16 v[2:5], v[182:185], v[220:223], v[2:5]
	s_barrier
	s_add_i32 s66, s66, 2
	s_add_u32 s0, s0, 0x100
	s_addc_u32 s1, s1, 0
	s_add_u32 s62, s62, 0x100
	s_addc_u32 s63, s63, 0
	s_cmp_gt_u32 s66, 29
	s_cbranch_scc0 .LBB0_762
	s_and_b64 vcc, exec, s[16:17]
	s_mov_b64 s[60:61], s[90:91]
	s_mov_b64 s[62:63], s[88:89]
	s_cbranch_vccz .LBB0_765
	s_barrier

; #define PG8_STAGE(bufoff, gbase, voff) do { _Pragma("unroll") for (int _i = 0; _i < 2; ++_i) \
;         __builtin_amdgcn_global_load_lds((const unsigned*)((const char*)(gbase) + (voff)[_i]), (PG8_LAS unsigned*)(lds + (bufoff) + ldsw + _i * 8192), 16, 0, 0); } while (0)
; #define PG8_LDA(dst, b, h) do { _Pragma("unroll") for (int m = 0; m < 4; ++m) _Pragma("unroll") for (int k = 0; k < 2; ++k) dst[m][k] = *(const PG8_LAS bf16x8*)(lds + PG8_SA(b, h) + aoff + m * 2048 + k * 1024); } while (0)
; #define PG8_LDB(dst, b, h) do { _Pragma("unroll") for (int n = 0; n < 2; ++n) _Pragma("unroll") for (int k = 0; k < 2; ++k) dst[n][k] = *(const PG8_LAS bf16x8*)(lds + PG8_SB(b, h) + boff + n * 2048 + k * 1024); } while (0)
; #define PG8_MMA(ai, bj, At, Bt) do { __builtin_amdgcn_s_setprio(1); _Pragma("unroll") for (int m = 0; m < 4; ++m) _Pragma("unroll") for (int n = 0; n < 2; ++n) _Pragma("unroll") for (int k = 0; k < 2; ++k) \
;         acc[ai][bj][m][n] = __builtin_amdgcn_mfma_f32_16x16x32_bf16(Bt[n][k], At[m][k], acc[ai][bj][m][n], 0, 0, 0); __builtin_amdgcn_s_setprio(0); } while (0)
; #define PG8_WAIT_V(n) asm volatile("s_waitcnt vmcnt(" #n ")" ::: "memory")
; #define PG8_WAIT_L(n) asm volatile("s_waitcnt lgkmcnt(" #n ")" ::: "memory")
; template <class Epi, class Sched, bool ALIGN_EPI = false, bool SP2 = false>
; __device__ __forceinline__ void gemm_phase(PG8_LAS unsigned char* lds, const Gemm g, const Sched& S, const Epi& E) {
;     ...
;             const bool last = (t == nt - 2);
;             const char* a1 = cA + (size_t)(t + 1) * kstep;
;             const char* a2 = last ? nA : cA + (size_t)(t + 2) * kstep; const char* b2 = last ? nB : cB + (size_t)(t + 2) * kstep;
;             const char* a3 = a2 + kstep; const char* b3 = b2 + kstep;
;             if (last && has_next) S.a_ready(nxt);
;             if constexpr (SP2) {
;             PG8_LDB(B0, 0, 0); PG8_LDB(B1, 0, 1); PG8_SCHED; PG8_LDA(At, 0, 0); PG8_STAGE(PG8_SA(1, 1), a1 + hstep, voffA);
;             PG8_WAIT_V(8); PG8_WAIT_L(0); PG8_BAR; PG8_MMA(0, 0, At, B0); PG8_MMA(0, 1, At, B1); PG8_BAR; PG8_SCHED;
;             PG8_LDA(At, 0, 1); PG8_STAGE(PG8_SB(0, 0), b2, voffB); PG8_STAGE(PG8_SB(0, 1), b2 + hstep, voffB); PG8_STAGE(PG8_SA(0, 0), a2, voffA);
;             PG8_WAIT_V(8); PG8_WAIT_L(0); PG8_BAR; PG8_MMA(1, 0, At, B0); PG8_MMA(1, 1, At, B1); PG8_BAR; PG8_SCHED;
.LBB0_842:
	s_add_u32 s30, s0, 0xffe00080
	s_addc_u32 s31, s1, -1
	s_add_i32 s68, 0, 0x10000
	s_cmpk_eq_i32 s67, 0x7c
	s_cselect_b32 s37, s23, s31
	s_cselect_b32 s36, s61, s30
	s_cselect_b32 s31, s19, s66
	s_cselect_b32 s30, s62, s63
	s_add_i32 s70, 0, 0x14000
	ds_read_b128 v[130:133], v244
	ds_read_b128 v[134:137], v244 offset:1024
	ds_read_b128 v[138:141], v244 offset:2048
	ds_read_b128 v[142:145], v244 offset:3072
	ds_read_b128 v[146:149], v245
	ds_read_b128 v[150:153], v245 offset:1024
	ds_read_b128 v[154:157], v245 offset:2048
	ds_read_b128 v[162:165], v245 offset:3072
	s_add_u32 s98, s0, 0xffe00000
	s_addc_u32 s99, s1, -1
	s_mov_b32 m0, s56
	s_nop 0
	global_load_lds_dwordx4 v172, s[98:99]
	s_mov_b32 m0, s57
	s_nop 0
	global_load_lds_dwordx4 v174, s[98:99]
	s_add_i32 m0, s51, 0xc000
	ds_read_b128 v[176:179], v201
	ds_read_b128 v[180:183], v201 offset:1024
	ds_read_b128 v[184:187], v201 offset:2048
	ds_read_b128 v[188:191], v201 offset:3072
	ds_read_b128 v[202:205], v201 offset:4096
	ds_read_b128 v[206:209], v201 offset:5120
	ds_read_b128 v[210:213], v201 offset:6144
	ds_read_b128 v[214:217], v201 offset:7168
	global_load_lds_dwordx4 v172, s[0:1]
	s_add_i32 m0, s51, 0xe000
	s_nop 0
	global_load_lds_dwordx4 v174, s[0:1]
	s_waitcnt vmcnt(8)
	s_waitcnt lgkmcnt(0)
	s_barrier
	v_mfma_f32_16x16x32_bf16 v[126:129], v[130:133], v[176:179], v[126:129]
	v_mfma_f32_16x16x32_bf16 v[122:125], v[138:141], v[176:179], v[122:125]
	v_mfma_f32_16x16x32_bf16 v[110:113], v[130:133], v[184:187], v[110:113]
	v_mfma_f32_16x16x32_bf16 v[106:109], v[138:141], v[184:187], v[106:109]
	v_mfma_f32_16x16x32_bf16 v[94:97], v[130:133], v[202:205], v[94:97]
	v_mfma_f32_16x16x32_bf16 v[90:93], v[138:141], v[202:205], v[90:93]
	v_mfma_f32_16x16x32_bf16 v[78:81], v[130:133], v[210:213], v[78:81]
	v_mfma_f32_16x16x32_bf16 v[74:77], v[138:141], v[210:213], v[74:77]
	v_mfma_f32_16x16x32_bf16 v[126:129], v[134:137], v[180:183], v[126:129]
	v_mfma_f32_16x16x32_bf16 v[122:125], v[142:145], v[180:183], v[122:125]
	v_mfma_f32_16x16x32_bf16 v[110:113], v[134:137], v[188:191], v[110:113]
	v_mfma_f32_16x16x32_bf16 v[106:109], v[142:145], v[188:191], v[106:109]
	v_mfma_f32_16x16x32_bf16 v[94:97], v[134:137], v[206:209], v[94:97]
	v_mfma_f32_16x16x32_bf16 v[90:93], v[142:145], v[206:209], v[90:93]
	v_mfma_f32_16x16x32_bf16 v[78:81], v[134:137], v[214:217], v[78:81]
	v_mfma_f32_16x16x32_bf16 v[74:77], v[142:145], v[214:217], v[74:77]
	v_mfma_f32_16x16x32_bf16 v[118:121], v[146:149], v[176:179], v[118:121]
	v_mfma_f32_16x16x32_bf16 v[114:117], v[154:157], v[176:179], v[114:117]
	v_mfma_f32_16x16x32_bf16 v[102:105], v[146:149], v[184:187], v[102:105]
	v_mfma_f32_16x16x32_bf16 v[98:101], v[154:157], v[184:187], v[98:101]
	v_mfma_f32_16x16x32_bf16 v[86:89], v[146:149], v[202:205], v[86:89]
	v_mfma_f32_16x16x32_bf16 v[82:85], v[154:157], v[202:205], v[82:85]
	v_mfma_f32_16x16x32_bf16 v[70:73], v[146:149], v[210:213], v[70:73]
	v_mfma_f32_16x16x32_bf16 v[66:69], v[154:157], v[210:213], v[66:69]
	v_mfma_f32_16x16x32_bf16 v[118:121], v[150:153], v[180:183], v[118:121]
	v_mfma_f32_16x16x32_bf16 v[114:117], v[162:165], v[180:183], v[114:117]
	v_mfma_f32_16x16x32_bf16 v[102:105], v[150:153], v[188:191], v[102:105]
	v_mfma_f32_16x16x32_bf16 v[98:101], v[162:165], v[188:191], v[98:101]
	v_mfma_f32_16x16x32_bf16 v[86:89], v[150:153], v[206:209], v[86:89]
	v_mfma_f32_16x16x32_bf16 v[82:85], v[162:165], v[206:209], v[82:85]
	v_mfma_f32_16x16x32_bf16 v[70:73], v[150:153], v[214:217], v[70:73]
	v_mfma_f32_16x16x32_bf16 v[66:69], v[162:165], v[214:217], v[66:69]
	s_barrier
	s_add_i32 s68, s68, s50
	s_mov_b32 m0, s68
	ds_read_b128 v[176:179], v201 offset:16384
	ds_read_b128 v[180:183], v201 offset:17408
	ds_read_b128 v[184:187], v201 offset:18432
	ds_read_b128 v[188:191], v201 offset:19456
	ds_read_b128 v[202:205], v201 offset:20480
	ds_read_b128 v[206:209], v201 offset:21504
	ds_read_b128 v[210:213], v201 offset:22528
	ds_read_b128 v[214:217], v201 offset:23552
	global_load_lds_dwordx4 v158, s[30:31]
	s_add_i32 m0, s68, 0x2000
	s_add_u32 s68, s30, 0x200000
	s_addc_u32 s69, s31, 0
	s_add_i32 s70, s70, s50
	global_load_lds_dwordx4 v166, s[30:31]
	s_mov_b32 m0, s70
	s_nop 0
	global_load_lds_dwordx4 v158, s[68:69]
	s_add_i32 m0, s70, 0x2000
	s_nop 0
	global_load_lds_dwordx4 v166, s[68:69]
	s_waitcnt vmcnt(6)
	s_waitcnt lgkmcnt(0)
	s_barrier
	v_mfma_f32_16x16x32_bf16 v[62:65], v[130:133], v[176:179], v[62:65]
	v_mfma_f32_16x16x32_bf16 v[58:61], v[138:141], v[176:179], v[58:61]
	v_mfma_f32_16x16x32_bf16 v[46:49], v[130:133], v[184:187], v[46:49]
	v_mfma_f32_16x16x32_bf16 v[42:45], v[138:141], v[184:187], v[42:45]
	v_mfma_f32_16x16x32_bf16 v[30:33], v[130:133], v[202:205], v[30:33]
	v_mfma_f32_16x16x32_bf16 v[26:29], v[138:141], v[202:205], v[26:29]
	v_mfma_f32_16x16x32_bf16 v[14:17], v[130:133], v[210:213], v[14:17]
	v_mfma_f32_16x16x32_bf16 v[10:13], v[138:141], v[210:213], v[10:13]
	v_mfma_f32_16x16x32_bf16 v[62:65], v[134:137], v[180:183], v[62:65]
	v_mfma_f32_16x16x32_bf16 v[58:61], v[142:145], v[180:183], v[58:61]
	v_mfma_f32_16x16x32_bf16 v[46:49], v[134:137], v[188:191], v[46:49]
	v_mfma_f32_16x16x32_bf16 v[42:45], v[142:145], v[188:191], v[42:45]
	v_mfma_f32_16x16x32_bf16 v[30:33], v[134:137], v[206:209], v[30:33]
	v_mfma_f32_16x16x32_bf16 v[26:29], v[142:145], v[206:209], v[26:29]
	v_mfma_f32_16x16x32_bf16 v[14:17], v[134:137], v[214:217], v[14:17]
	v_mfma_f32_16x16x32_bf16 v[10:13], v[142:145], v[214:217], v[10:13]
	v_mfma_f32_16x16x32_bf16 v[54:57], v[146:149], v[176:179], v[54:57]
	v_mfma_f32_16x16x32_bf16 v[50:53], v[154:157], v[176:179], v[50:53]
	v_mfma_f32_16x16x32_bf16 v[38:41], v[146:149], v[184:187], v[38:41]
	v_mfma_f32_16x16x32_bf16 v[34:37], v[154:157], v[184:187], v[34:37]
	v_mfma_f32_16x16x32_bf16 v[22:25], v[146:149], v[202:205], v[22:25]
	v_mfma_f32_16x16x32_bf16 v[18:21], v[154:157], v[202:205], v[18:21]
	v_mfma_f32_16x16x32_bf16 v[6:9], v[146:149], v[210:213], v[6:9]
	v_mfma_f32_16x16x32_bf16 v[2:5], v[154:157], v[210:213], v[2:5]
	v_mfma_f32_16x16x32_bf16 v[54:57], v[150:153], v[180:183], v[54:57]
	v_mfma_f32_16x16x32_bf16 v[50:53], v[162:165], v[180:183], v[50:53]
	v_mfma_f32_16x16x32_bf16 v[38:41], v[150:153], v[188:191], v[38:41]
	v_mfma_f32_16x16x32_bf16 v[34:37], v[162:165], v[188:191], v[34:37]
	v_mfma_f32_16x16x32_bf16 v[22:25], v[150:153], v[206:209], v[22:25]
	v_mfma_f32_16x16x32_bf16 v[18:21], v[162:165], v[206:209], v[18:21]
	v_mfma_f32_16x16x32_bf16 v[6:9], v[150:153], v[214:217], v[6:9]
	v_mfma_f32_16x16x32_bf16 v[2:5], v[162:165], v[214:217], v[2:5]
	s_barrier
; #define PG8_STAGE(bufoff, gbase, voff) do { _Pragma("unroll") for (int _i = 0; _i < 2; ++_i) \
;         __builtin_amdgcn_global_load_lds((const unsigned*)((const char*)(gbase) + (voff)[_i]), (PG8_LAS unsigned*)(lds + (bufoff) + ldsw + _i * 8192), 16, 0, 0); } while (0)
; #define PG8_LDA(dst, b, h) do { _Pragma("unroll") for (int m = 0; m < 4; ++m) _Pragma("unroll") for (int k = 0; k < 2; ++k) dst[m][k] = *(const PG8_LAS bf16x8*)(lds + PG8_SA(b, h) + aoff + m * 2048 + k * 1024); } while (0)
; #define PG8_LDB(dst, b, h) do { _Pragma("unroll") for (int n = 0; n < 2; ++n) _Pragma("unroll") for (int k = 0; k < 2; ++k) dst[n][k] = *(const PG8_LAS bf16x8*)(lds + PG8_SB(b, h) + boff + n * 2048 + k * 1024); } while (0)
; #define PG8_MMA(ai, bj, At, Bt) do { __builtin_amdgcn_s_setprio(1); _Pragma("unroll") for (int m = 0; m < 4; ++m) _Pragma("unroll") for (int n = 0; n < 2; ++n) _Pragma("unroll") for (int k = 0; k < 2; ++k) \
;         acc[ai][bj][m][n] = __builtin_amdgcn_mfma_f32_16x16x32_bf16(Bt[n][k], At[m][k], acc[ai][bj][m][n], 0, 0, 0); __builtin_amdgcn_s_setprio(0); } while (0)
; #define PG8_WAIT_V(n) asm volatile("s_waitcnt vmcnt(" #n ")" ::: "memory")
; #define PG8_WAIT_L(n) asm volatile("s_waitcnt lgkmcnt(" #n ")" ::: "memory")
; #define PG8_BAR __builtin_amdgcn_s_barrier()
; #define PG8_SCHED __builtin_amdgcn_sched_barrier(0)
; template <class Epi, class Sched, bool ALIGN_EPI = false, bool SP2 = false>
; __device__ __forceinline__ void gemm_phase(PG8_LAS unsigned char* lds, const Gemm g, const Sched& S, const Epi& E) {
;     ...
;             PG8_LDB(B0, 1, 0); PG8_LDB(B1, 1, 1); PG8_SCHED; PG8_LDA(At, 1, 0); PG8_STAGE(PG8_SA(0, 1), a2 + hstep, voffA);
;             PG8_WAIT_V(8); PG8_WAIT_L(0); PG8_BAR; PG8_MMA(0, 0, At, B0); PG8_MMA(0, 1, At, B1); PG8_BAR; PG8_SCHED;
;             PG8_LDA(At, 1, 1); PG8_STAGE(PG8_SB(1, 0), b3, voffB); PG8_STAGE(PG8_SB(1, 1), b3 + hstep, voffB); PG8_STAGE(PG8_SA(1, 0), a3, voffA);
;             PG8_WAIT_V(8); PG8_WAIT_L(0); PG8_BAR; PG8_MMA(1, 0, At, B0); PG8_MMA(1, 1, At, B1); PG8_BAR; PG8_SCHED;
	s_add_i32 s68, 0, 0x18000
	s_add_i32 s69, 0, 0x1c000
	ds_read_b128 v[130:133], v246
	ds_read_b128 v[134:137], v246 offset:1024
	ds_read_b128 v[138:141], v246 offset:2048
	ds_read_b128 v[142:145], v246 offset:3072
	ds_read_b128 v[146:149], v247
	ds_read_b128 v[150:153], v247 offset:1024
	ds_read_b128 v[154:157], v247 offset:2048
	ds_read_b128 v[162:165], v247 offset:3072
	s_mov_b32 m0, s51
	s_nop 0
	global_load_lds_dwordx4 v170, s[36:37]
	s_mov_b32 m0, s52
	s_nop 0
	global_load_lds_dwordx4 v168, s[36:37]
	s_add_u32 s36, s36, 0x200000
	s_addc_u32 s37, s37, 0
	s_mov_b32 m0, s53
	ds_read_b128 v[176:179], v201 offset:32768
	ds_read_b128 v[180:183], v201 offset:33792
	ds_read_b128 v[184:187], v201 offset:34816
	ds_read_b128 v[188:191], v201 offset:35840
	ds_read_b128 v[202:205], v201 offset:36864
	ds_read_b128 v[206:209], v201 offset:37888
	ds_read_b128 v[210:213], v201 offset:38912
	ds_read_b128 v[214:217], v201 offset:39936
	global_load_lds_dwordx4 v170, s[36:37]
	s_mov_b32 m0, s54
	s_nop 0
	global_load_lds_dwordx4 v168, s[36:37]
	s_waitcnt vmcnt(8)
	s_waitcnt lgkmcnt(0)
	s_barrier
	v_mfma_f32_16x16x32_bf16 v[126:129], v[130:133], v[176:179], v[126:129]
	v_mfma_f32_16x16x32_bf16 v[122:125], v[138:141], v[176:179], v[122:125]
	v_mfma_f32_16x16x32_bf16 v[110:113], v[130:133], v[184:187], v[110:113]
	v_mfma_f32_16x16x32_bf16 v[106:109], v[138:141], v[184:187], v[106:109]
	v_mfma_f32_16x16x32_bf16 v[94:97], v[130:133], v[202:205], v[94:97]
	v_mfma_f32_16x16x32_bf16 v[90:93], v[138:141], v[202:205], v[90:93]
	v_mfma_f32_16x16x32_bf16 v[78:81], v[130:133], v[210:213], v[78:81]
	v_mfma_f32_16x16x32_bf16 v[74:77], v[138:141], v[210:213], v[74:77]
	v_mfma_f32_16x16x32_bf16 v[126:129], v[134:137], v[180:183], v[126:129]
	v_mfma_f32_16x16x32_bf16 v[122:125], v[142:145], v[180:183], v[122:125]
	v_mfma_f32_16x16x32_bf16 v[110:113], v[134:137], v[188:191], v[110:113]
	v_mfma_f32_16x16x32_bf16 v[106:109], v[142:145], v[188:191], v[106:109]
	v_mfma_f32_16x16x32_bf16 v[94:97], v[134:137], v[206:209], v[94:97]
	v_mfma_f32_16x16x32_bf16 v[90:93], v[142:145], v[206:209], v[90:93]
	v_mfma_f32_16x16x32_bf16 v[78:81], v[134:137], v[214:217], v[78:81]
	v_mfma_f32_16x16x32_bf16 v[74:77], v[142:145], v[214:217], v[74:77]
	v_mfma_f32_16x16x32_bf16 v[118:121], v[146:149], v[176:179], v[118:121]
	v_mfma_f32_16x16x32_bf16 v[114:117], v[154:157], v[176:179], v[114:117]
	v_mfma_f32_16x16x32_bf16 v[102:105], v[146:149], v[184:187], v[102:105]
	v_mfma_f32_16x16x32_bf16 v[98:101], v[154:157], v[184:187], v[98:101]
	v_mfma_f32_16x16x32_bf16 v[86:89], v[146:149], v[202:205], v[86:89]
	v_mfma_f32_16x16x32_bf16 v[82:85], v[154:157], v[202:205], v[82:85]
	v_mfma_f32_16x16x32_bf16 v[70:73], v[146:149], v[210:213], v[70:73]
	v_mfma_f32_16x16x32_bf16 v[66:69], v[154:157], v[210:213], v[66:69]
	v_mfma_f32_16x16x32_bf16 v[118:121], v[150:153], v[180:183], v[118:121]
	v_mfma_f32_16x16x32_bf16 v[114:117], v[162:165], v[180:183], v[114:117]
	v_mfma_f32_16x16x32_bf16 v[102:105], v[150:153], v[188:191], v[102:105]
	v_mfma_f32_16x16x32_bf16 v[98:101], v[162:165], v[188:191], v[98:101]
	v_mfma_f32_16x16x32_bf16 v[86:89], v[150:153], v[206:209], v[86:89]
	v_mfma_f32_16x16x32_bf16 v[82:85], v[162:165], v[206:209], v[82:85]
	v_mfma_f32_16x16x32_bf16 v[70:73], v[150:153], v[214:217], v[70:73]
	v_mfma_f32_16x16x32_bf16 v[66:69], v[162:165], v[214:217], v[66:69]
	s_barrier
	s_add_i32 s36, s68, s50
	s_add_i32 m0, s36, 0xffffff80
	ds_read_b128 v[176:179], v201 offset:49152
	ds_read_b128 v[180:183], v201 offset:50176
	ds_read_b128 v[184:187], v201 offset:51200
	ds_read_b128 v[188:191], v201 offset:52224
	ds_read_b128 v[202:205], v201 offset:53248
	ds_read_b128 v[206:209], v201 offset:54272
	ds_read_b128 v[210:213], v201 offset:55296
	ds_read_b128 v[214:217], v201 offset:56320
	global_load_lds_dwordx4 v158, s[30:31] offset:128
	s_add_i32 m0, s36, 0x1f80
	s_add_i32 s36, s69, s50
	global_load_lds_dwordx4 v166, s[30:31] offset:128
	s_add_u32 s30, s30, 0x200080
	s_addc_u32 s31, s31, 0
	s_mov_b32 m0, s36
	s_nop 0
	global_load_lds_dwordx4 v158, s[30:31]
	s_add_i32 m0, s36, 0x2000
	s_nop 0
	global_load_lds_dwordx4 v166, s[30:31]
	s_waitcnt vmcnt(6)
	s_waitcnt lgkmcnt(0)
	s_barrier
	v_mfma_f32_16x16x32_bf16 v[62:65], v[130:133], v[176:179], v[62:65]
	v_mfma_f32_16x16x32_bf16 v[58:61], v[138:141], v[176:179], v[58:61]
	v_mfma_f32_16x16x32_bf16 v[46:49], v[130:133], v[184:187], v[46:49]
	v_mfma_f32_16x16x32_bf16 v[42:45], v[138:141], v[184:187], v[42:45]
	v_mfma_f32_16x16x32_bf16 v[30:33], v[130:133], v[202:205], v[30:33]
	v_mfma_f32_16x16x32_bf16 v[26:29], v[138:141], v[202:205], v[26:29]
	v_mfma_f32_16x16x32_bf16 v[14:17], v[130:133], v[210:213], v[14:17]
	v_mfma_f32_16x16x32_bf16 v[10:13], v[138:141], v[210:213], v[10:13]
	v_mfma_f32_16x16x32_bf16 v[62:65], v[134:137], v[180:183], v[62:65]
	v_mfma_f32_16x16x32_bf16 v[58:61], v[142:145], v[180:183], v[58:61]
	v_mfma_f32_16x16x32_bf16 v[46:49], v[134:137], v[188:191], v[46:49]
	v_mfma_f32_16x16x32_bf16 v[42:45], v[142:145], v[188:191], v[42:45]
	v_mfma_f32_16x16x32_bf16 v[30:33], v[134:137], v[206:209], v[30:33]
	v_mfma_f32_16x16x32_bf16 v[26:29], v[142:145], v[206:209], v[26:29]
	v_mfma_f32_16x16x32_bf16 v[14:17], v[134:137], v[214:217], v[14:17]
	v_mfma_f32_16x16x32_bf16 v[10:13], v[142:145], v[214:217], v[10:13]
	v_mfma_f32_16x16x32_bf16 v[54:57], v[146:149], v[176:179], v[54:57]
	v_mfma_f32_16x16x32_bf16 v[50:53], v[154:157], v[176:179], v[50:53]
	v_mfma_f32_16x16x32_bf16 v[38:41], v[146:149], v[184:187], v[38:41]
	v_mfma_f32_16x16x32_bf16 v[34:37], v[154:157], v[184:187], v[34:37]
	v_mfma_f32_16x16x32_bf16 v[22:25], v[146:149], v[202:205], v[22:25]
	v_mfma_f32_16x16x32_bf16 v[18:21], v[154:157], v[202:205], v[18:21]
	v_mfma_f32_16x16x32_bf16 v[6:9], v[146:149], v[210:213], v[6:9]
	v_mfma_f32_16x16x32_bf16 v[2:5], v[154:157], v[210:213], v[2:5]
	v_mfma_f32_16x16x32_bf16 v[54:57], v[150:153], v[180:183], v[54:57]
	v_mfma_f32_16x16x32_bf16 v[50:53], v[162:165], v[180:183], v[50:53]
	v_mfma_f32_16x16x32_bf16 v[38:41], v[150:153], v[188:191], v[38:41]
	v_mfma_f32_16x16x32_bf16 v[34:37], v[162:165], v[188:191], v[34:37]
	v_mfma_f32_16x16x32_bf16 v[22:25], v[150:153], v[206:209], v[22:25]
	v_mfma_f32_16x16x32_bf16 v[18:21], v[162:165], v[206:209], v[18:21]
	v_mfma_f32_16x16x32_bf16 v[6:9], v[150:153], v[214:217], v[6:9]
	v_mfma_f32_16x16x32_bf16 v[2:5], v[162:165], v[214:217], v[2:5]
	s_barrier
	s_add_i32 s67, s67, 2
	s_add_u32 s0, s0, 0x100
	s_addc_u32 s1, s1, 0
	s_add_u32 s63, s63, 0x100
	s_addc_u32 s66, s66, 0
	s_cmpk_gt_u32 s67, 0x7d
	s_cbranch_scc0 .LBB0_842
	s_and_b64 vcc, exec, s[16:17]
	s_cbranch_vccz .LBB0_845
	s_barrier

; #define PG8_STAGE(bufoff, gbase, voff) do { _Pragma("unroll") for (int _i = 0; _i < 2; ++_i) \
;         __builtin_amdgcn_global_load_lds((const unsigned*)((const char*)(gbase) + (voff)[_i]), (PG8_LAS unsigned*)(lds + (bufoff) + ldsw + _i * 8192), 16, 0, 0); } while (0)
; #define PG8_LDA(dst, b, h) do { _Pragma("unroll") for (int m = 0; m < 4; ++m) _Pragma("unroll") for (int k = 0; k < 2; ++k) dst[m][k] = *(const PG8_LAS bf16x8*)(lds + PG8_SA(b, h) + aoff + m * 2048 + k * 1024); } while (0)
; #define PG8_LDB(dst, b, h) do { _Pragma("unroll") for (int n = 0; n < 2; ++n) _Pragma("unroll") for (int k = 0; k < 2; ++k) dst[n][k] = *(const PG8_LAS bf16x8*)(lds + PG8_SB(b, h) + boff + n * 2048 + k * 1024); } while (0)
; #define PG8_MMA(ai, bj, At, Bt) do { __builtin_amdgcn_s_setprio(1); _Pragma("unroll") for (int m = 0; m < 4; ++m) _Pragma("unroll") for (int n = 0; n < 2; ++n) _Pragma("unroll") for (int k = 0; k < 2; ++k) \
;         acc[ai][bj][m][n] = __builtin_amdgcn_mfma_f32_16x16x32_bf16(Bt[n][k], At[m][k], acc[ai][bj][m][n], 0, 0, 0); __builtin_amdgcn_s_setprio(0); } while (0)
; #define PG8_WAIT_V(n) asm volatile("s_waitcnt vmcnt(" #n ")" ::: "memory")
; #define PG8_WAIT_L(n) asm volatile("s_waitcnt lgkmcnt(" #n ")" ::: "memory")
; template <class Epi, class Sched, bool ALIGN_EPI = false, bool SP2 = false>
; __device__ __forceinline__ void gemm_phase(PG8_LAS unsigned char* lds, const Gemm g, const Sched& S, const Epi& E) {
;     ...
;             const bool last = (t == nt - 2);
;             const char* a1 = cA + (size_t)(t + 1) * kstep;
;             const char* a2 = last ? nA : cA + (size_t)(t + 2) * kstep; const char* b2 = last ? nB : cB + (size_t)(t + 2) * kstep;
;             const char* a3 = a2 + kstep; const char* b3 = b2 + kstep;
;             if (last && has_next) S.a_ready(nxt);
;             if constexpr (SP2) {
;             PG8_LDB(B0, 0, 0); PG8_LDB(B1, 0, 1); PG8_SCHED; PG8_LDA(At, 0, 0); PG8_STAGE(PG8_SA(1, 1), a1 + hstep, voffA);
;             PG8_WAIT_V(8); PG8_WAIT_L(0); PG8_BAR; PG8_MMA(0, 0, At, B0); PG8_MMA(0, 1, At, B1); PG8_BAR; PG8_SCHED;
;             PG8_LDA(At, 0, 1); PG8_STAGE(PG8_SB(0, 0), b2, voffB); PG8_STAGE(PG8_SB(0, 1), b2 + hstep, voffB); PG8_STAGE(PG8_SA(0, 0), a2, voffA);
;             PG8_WAIT_V(8); PG8_WAIT_L(0); PG8_BAR; PG8_MMA(1, 0, At, B0); PG8_MMA(1, 1, At, B1); PG8_BAR; PG8_SCHED;
.LBB0_880:
	s_add_u32 s28, s0, 0xffe00080
	s_addc_u32 s29, s1, -1
	s_add_i32 s59, 0, 0x10000
	s_cmpk_eq_i32 s58, 0x7c
	s_cselect_b32 s31, s19, s29
	s_cselect_b32 s30, s54, s28
	s_cselect_b32 s29, s17, s57
	s_cselect_b32 s28, s55, s56
	s_add_i32 s62, 0, 0x14000
	ds_read_b128 v[130:133], v244
	ds_read_b128 v[134:137], v244 offset:1024
	ds_read_b128 v[138:141], v244 offset:2048
	ds_read_b128 v[142:145], v244 offset:3072
	ds_read_b128 v[146:149], v245
	ds_read_b128 v[162:165], v245 offset:1024
	ds_read_b128 v[168:171], v245 offset:2048
	ds_read_b128 v[172:175], v245 offset:3072
	s_add_u32 s98, s0, 0xffe00000
	s_addc_u32 s99, s1, -1
	s_mov_b32 m0, s44
	s_nop 0
	global_load_lds_dwordx4 v156, s[98:99]
	s_mov_b32 m0, s45
	s_nop 0
	global_load_lds_dwordx4 v166, s[98:99]
	s_add_i32 m0, s36, 0xc000
	ds_read_b128 v[182:185], v180
	ds_read_b128 v[186:189], v180 offset:1024
	ds_read_b128 v[190:193], v180 offset:2048
	ds_read_b128 v[200:203], v180 offset:3072
	ds_read_b128 v[204:207], v180 offset:4096
	ds_read_b128 v[208:211], v180 offset:5120
	ds_read_b128 v[212:215], v180 offset:6144
	ds_read_b128 v[216:219], v180 offset:7168
	global_load_lds_dwordx4 v156, s[0:1]
	s_add_i32 m0, s36, 0xe000
	s_nop 0
	global_load_lds_dwordx4 v166, s[0:1]
	s_waitcnt vmcnt(8)
	s_waitcnt lgkmcnt(0)
	s_barrier
	v_mfma_f32_16x16x32_bf16 v[126:129], v[130:133], v[182:185], v[126:129]
	v_mfma_f32_16x16x32_bf16 v[122:125], v[138:141], v[182:185], v[122:125]
	v_mfma_f32_16x16x32_bf16 v[118:121], v[130:133], v[190:193], v[118:121]
	v_mfma_f32_16x16x32_bf16 v[114:117], v[138:141], v[190:193], v[114:117]
	v_mfma_f32_16x16x32_bf16 v[94:97], v[130:133], v[204:207], v[94:97]
	v_mfma_f32_16x16x32_bf16 v[90:93], v[138:141], v[204:207], v[90:93]
	v_mfma_f32_16x16x32_bf16 v[82:85], v[130:133], v[212:215], v[82:85]
	v_mfma_f32_16x16x32_bf16 v[74:77], v[138:141], v[212:215], v[74:77]
	v_mfma_f32_16x16x32_bf16 v[126:129], v[134:137], v[186:189], v[126:129]
	v_mfma_f32_16x16x32_bf16 v[122:125], v[142:145], v[186:189], v[122:125]
	v_mfma_f32_16x16x32_bf16 v[118:121], v[134:137], v[200:203], v[118:121]
	v_mfma_f32_16x16x32_bf16 v[114:117], v[142:145], v[200:203], v[114:117]
	v_mfma_f32_16x16x32_bf16 v[94:97], v[134:137], v[208:211], v[94:97]
	v_mfma_f32_16x16x32_bf16 v[90:93], v[142:145], v[208:211], v[90:93]
	v_mfma_f32_16x16x32_bf16 v[82:85], v[134:137], v[216:219], v[82:85]
	v_mfma_f32_16x16x32_bf16 v[74:77], v[142:145], v[216:219], v[74:77]
	v_mfma_f32_16x16x32_bf16 v[110:113], v[146:149], v[182:185], v[110:113]
	v_mfma_f32_16x16x32_bf16 v[106:109], v[168:171], v[182:185], v[106:109]
	v_mfma_f32_16x16x32_bf16 v[102:105], v[146:149], v[190:193], v[102:105]
	v_mfma_f32_16x16x32_bf16 v[98:101], v[168:171], v[190:193], v[98:101]
	v_mfma_f32_16x16x32_bf16 v[86:89], v[146:149], v[204:207], v[86:89]
	v_mfma_f32_16x16x32_bf16 v[78:81], v[168:171], v[204:207], v[78:81]
	v_mfma_f32_16x16x32_bf16 v[70:73], v[146:149], v[212:215], v[70:73]
	v_mfma_f32_16x16x32_bf16 v[66:69], v[168:171], v[212:215], v[66:69]
	v_mfma_f32_16x16x32_bf16 v[110:113], v[162:165], v[186:189], v[110:113]
	v_mfma_f32_16x16x32_bf16 v[106:109], v[172:175], v[186:189], v[106:109]
	v_mfma_f32_16x16x32_bf16 v[102:105], v[162:165], v[200:203], v[102:105]
	v_mfma_f32_16x16x32_bf16 v[98:101], v[172:175], v[200:203], v[98:101]
	v_mfma_f32_16x16x32_bf16 v[86:89], v[162:165], v[208:211], v[86:89]
	v_mfma_f32_16x16x32_bf16 v[78:81], v[172:175], v[208:211], v[78:81]
	v_mfma_f32_16x16x32_bf16 v[70:73], v[162:165], v[216:219], v[70:73]
	v_mfma_f32_16x16x32_bf16 v[66:69], v[172:175], v[216:219], v[66:69]
	s_barrier
	s_add_i32 s59, s59, s34
	s_mov_b32 m0, s59
	ds_read_b128 v[182:185], v180 offset:16384
	ds_read_b128 v[186:189], v180 offset:17408
	ds_read_b128 v[190:193], v180 offset:18432
	ds_read_b128 v[200:203], v180 offset:19456
	ds_read_b128 v[204:207], v180 offset:20480
	ds_read_b128 v[208:211], v180 offset:21504
	ds_read_b128 v[212:215], v180 offset:22528
	ds_read_b128 v[216:219], v180 offset:23552
	global_load_lds_dwordx4 v158, s[28:29]
	s_add_i32 m0, s59, 0x2000
	s_add_u32 s60, s28, 0x200000
	s_addc_u32 s61, s29, 0
	s_add_i32 s59, s62, s34
	global_load_lds_dwordx4 v150, s[28:29]
	s_mov_b32 m0, s59
	s_nop 0
	global_load_lds_dwordx4 v158, s[60:61]
	s_add_i32 m0, s59, 0x2000
	s_nop 0
	global_load_lds_dwordx4 v150, s[60:61]
	s_waitcnt vmcnt(6)
	s_waitcnt lgkmcnt(0)
	s_barrier
	v_mfma_f32_16x16x32_bf16 v[62:65], v[130:133], v[182:185], v[62:65]
	v_mfma_f32_16x16x32_bf16 v[58:61], v[138:141], v[182:185], v[58:61]
	v_mfma_f32_16x16x32_bf16 v[50:53], v[130:133], v[190:193], v[50:53]
	v_mfma_f32_16x16x32_bf16 v[42:45], v[138:141], v[190:193], v[42:45]
	v_mfma_f32_16x16x32_bf16 v[34:37], v[130:133], v[204:207], v[34:37]
	v_mfma_f32_16x16x32_bf16 v[26:29], v[138:141], v[204:207], v[26:29]
	v_mfma_f32_16x16x32_bf16 v[18:21], v[130:133], v[212:215], v[18:21]
	v_mfma_f32_16x16x32_bf16 v[10:13], v[138:141], v[212:215], v[10:13]
	v_mfma_f32_16x16x32_bf16 v[62:65], v[134:137], v[186:189], v[62:65]
	v_mfma_f32_16x16x32_bf16 v[58:61], v[142:145], v[186:189], v[58:61]
	v_mfma_f32_16x16x32_bf16 v[50:53], v[134:137], v[200:203], v[50:53]
	v_mfma_f32_16x16x32_bf16 v[42:45], v[142:145], v[200:203], v[42:45]
	v_mfma_f32_16x16x32_bf16 v[34:37], v[134:137], v[208:211], v[34:37]
	v_mfma_f32_16x16x32_bf16 v[26:29], v[142:145], v[208:211], v[26:29]
	v_mfma_f32_16x16x32_bf16 v[18:21], v[134:137], v[216:219], v[18:21]
	v_mfma_f32_16x16x32_bf16 v[10:13], v[142:145], v[216:219], v[10:13]
	v_mfma_f32_16x16x32_bf16 v[54:57], v[146:149], v[182:185], v[54:57]
	v_mfma_f32_16x16x32_bf16 v[46:49], v[168:171], v[182:185], v[46:49]
	v_mfma_f32_16x16x32_bf16 v[38:41], v[146:149], v[190:193], v[38:41]
	v_mfma_f32_16x16x32_bf16 v[30:33], v[168:171], v[190:193], v[30:33]
	v_mfma_f32_16x16x32_bf16 v[22:25], v[146:149], v[204:207], v[22:25]
	v_mfma_f32_16x16x32_bf16 v[14:17], v[168:171], v[204:207], v[14:17]
	v_mfma_f32_16x16x32_bf16 v[6:9], v[146:149], v[212:215], v[6:9]
	v_mfma_f32_16x16x32_bf16 v[2:5], v[168:171], v[212:215], v[2:5]
	v_mfma_f32_16x16x32_bf16 v[54:57], v[162:165], v[186:189], v[54:57]
	v_mfma_f32_16x16x32_bf16 v[46:49], v[172:175], v[186:189], v[46:49]
	v_mfma_f32_16x16x32_bf16 v[38:41], v[162:165], v[200:203], v[38:41]
	v_mfma_f32_16x16x32_bf16 v[30:33], v[172:175], v[200:203], v[30:33]
	v_mfma_f32_16x16x32_bf16 v[22:25], v[162:165], v[208:211], v[22:25]
	v_mfma_f32_16x16x32_bf16 v[14:17], v[172:175], v[208:211], v[14:17]
	v_mfma_f32_16x16x32_bf16 v[6:9], v[162:165], v[216:219], v[6:9]
	v_mfma_f32_16x16x32_bf16 v[2:5], v[172:175], v[216:219], v[2:5]
	s_barrier
; #define PG8_STAGE(bufoff, gbase, voff) do { _Pragma("unroll") for (int _i = 0; _i < 2; ++_i) \
;         __builtin_amdgcn_global_load_lds((const unsigned*)((const char*)(gbase) + (voff)[_i]), (PG8_LAS unsigned*)(lds + (bufoff) + ldsw + _i * 8192), 16, 0, 0); } while (0)
; #define PG8_LDA(dst, b, h) do { _Pragma("unroll") for (int m = 0; m < 4; ++m) _Pragma("unroll") for (int k = 0; k < 2; ++k) dst[m][k] = *(const PG8_LAS bf16x8*)(lds + PG8_SA(b, h) + aoff + m * 2048 + k * 1024); } while (0)
; #define PG8_WAIT_V(n) asm volatile("s_waitcnt vmcnt(" #n ")" ::: "memory")
; #define PG8_WAIT_L(n) asm volatile("s_waitcnt lgkmcnt(" #n ")" ::: "memory")
; template <class Epi, class Sched, bool ALIGN_EPI = false, bool SP2 = false>
; __device__ __forceinline__ void gemm_phase(PG8_LAS unsigned char* lds, const Gemm g, const Sched& S, const Epi& E) {
;     ...
;         for (int t = 0; t < nt; t += 2) {
;             const bool last = (t == nt - 2);
;             const char* a1 = cA + (size_t)(t + 1) * kstep;
;             const char* a2 = last ? nA : cA + (size_t)(t + 2) * kstep; const char* b2 = last ? nB : cB + (size_t)(t + 2) * kstep;
;             const char* a3 = a2 + kstep; const char* b3 = b2 + kstep;
;             if (last && has_next) S.a_ready(nxt);
;             if constexpr (SP2) {
;             PG8_LDB(B0, 0, 0); PG8_LDB(B1, 0, 1); PG8_SCHED; PG8_LDA(At, 0, 0); PG8_STAGE(PG8_SA(1, 1), a1 + hstep, voffA);
;             PG8_WAIT_V(8); PG8_WAIT_L(0); PG8_BAR; PG8_MMA(0, 0, At, B0); PG8_MMA(0, 1, At, B1); PG8_BAR; PG8_SCHED;
;             PG8_LDA(At, 0, 1); PG8_STAGE(PG8_SB(0, 0), b2, voffB); PG8_STAGE(PG8_SB(0, 1), b2 + hstep, voffB); PG8_STAGE(PG8_SA(0, 0), a2, voffA);
;             PG8_WAIT_V(8); PG8_WAIT_L(0); PG8_BAR; PG8_MMA(1, 0, At, B0); PG8_MMA(1, 1, At, B1); PG8_BAR; PG8_SCHED;
;             PG8_LDB(B0, 1, 0); PG8_LDB(B1, 1, 1); PG8_SCHED; PG8_LDA(At, 1, 0); PG8_STAGE(PG8_SA(0, 1), a2 + hstep, voffA);
;             PG8_WAIT_V(8); PG8_WAIT_L(0); PG8_BAR; PG8_MMA(0, 0, At, B0); PG8_MMA(0, 1, At, B1); PG8_BAR; PG8_SCHED;
;             PG8_LDA(At, 1, 1); PG8_STAGE(PG8_SB(1, 0), b3, voffB); PG8_STAGE(PG8_SB(1, 1), b3 + hstep, voffB); PG8_STAGE(PG8_SA(1, 0), a3, voffA);
;             PG8_WAIT_V(8); PG8_WAIT_L(0); PG8_BAR; PG8_MMA(1, 0, At, B0); PG8_MMA(1, 1, At, B1); PG8_BAR; PG8_SCHED;
;     ...
;         if constexpr (ALIGN_EPI) { if (wr == 0) PG8_BAR; }
	s_add_i32 s59, 0, 0x18000
	s_add_i32 s60, 0, 0x1c000
	ds_read_b128 v[130:133], v246
	ds_read_b128 v[134:137], v246 offset:1024
	ds_read_b128 v[138:141], v246 offset:2048
	ds_read_b128 v[142:145], v246 offset:3072
	ds_read_b128 v[146:149], v247
	ds_read_b128 v[162:165], v247 offset:1024
	ds_read_b128 v[168:171], v247 offset:2048
	ds_read_b128 v[172:175], v247 offset:3072
	s_mov_b32 m0, s36
	s_nop 0
	global_load_lds_dwordx4 v154, s[30:31]
	s_mov_b32 m0, s37
	s_nop 0
	global_load_lds_dwordx4 v152, s[30:31]
	s_add_u32 s30, s30, 0x200000
	s_addc_u32 s31, s31, 0
	s_mov_b32 m0, s42
	ds_read_b128 v[182:185], v180 offset:32768
	ds_read_b128 v[186:189], v180 offset:33792
	ds_read_b128 v[190:193], v180 offset:34816
	ds_read_b128 v[200:203], v180 offset:35840
	ds_read_b128 v[204:207], v180 offset:36864
	ds_read_b128 v[208:211], v180 offset:37888
	ds_read_b128 v[212:215], v180 offset:38912
	ds_read_b128 v[216:219], v180 offset:39936
	global_load_lds_dwordx4 v154, s[30:31]
	s_mov_b32 m0, s43
	s_nop 0
	global_load_lds_dwordx4 v152, s[30:31]
	s_waitcnt vmcnt(8)
	s_waitcnt lgkmcnt(0)
	s_barrier
	v_mfma_f32_16x16x32_bf16 v[126:129], v[130:133], v[182:185], v[126:129]
	v_mfma_f32_16x16x32_bf16 v[122:125], v[138:141], v[182:185], v[122:125]
	v_mfma_f32_16x16x32_bf16 v[118:121], v[130:133], v[190:193], v[118:121]
	v_mfma_f32_16x16x32_bf16 v[114:117], v[138:141], v[190:193], v[114:117]
	v_mfma_f32_16x16x32_bf16 v[94:97], v[130:133], v[204:207], v[94:97]
	v_mfma_f32_16x16x32_bf16 v[90:93], v[138:141], v[204:207], v[90:93]
	v_mfma_f32_16x16x32_bf16 v[82:85], v[130:133], v[212:215], v[82:85]
	v_mfma_f32_16x16x32_bf16 v[74:77], v[138:141], v[212:215], v[74:77]
	v_mfma_f32_16x16x32_bf16 v[126:129], v[134:137], v[186:189], v[126:129]
	v_mfma_f32_16x16x32_bf16 v[122:125], v[142:145], v[186:189], v[122:125]
	v_mfma_f32_16x16x32_bf16 v[118:121], v[134:137], v[200:203], v[118:121]
	v_mfma_f32_16x16x32_bf16 v[114:117], v[142:145], v[200:203], v[114:117]
	v_mfma_f32_16x16x32_bf16 v[94:97], v[134:137], v[208:211], v[94:97]
	v_mfma_f32_16x16x32_bf16 v[90:93], v[142:145], v[208:211], v[90:93]
	v_mfma_f32_16x16x32_bf16 v[82:85], v[134:137], v[216:219], v[82:85]
	v_mfma_f32_16x16x32_bf16 v[74:77], v[142:145], v[216:219], v[74:77]
	v_mfma_f32_16x16x32_bf16 v[110:113], v[146:149], v[182:185], v[110:113]
	v_mfma_f32_16x16x32_bf16 v[106:109], v[168:171], v[182:185], v[106:109]
	v_mfma_f32_16x16x32_bf16 v[102:105], v[146:149], v[190:193], v[102:105]
	v_mfma_f32_16x16x32_bf16 v[98:101], v[168:171], v[190:193], v[98:101]
	v_mfma_f32_16x16x32_bf16 v[86:89], v[146:149], v[204:207], v[86:89]
	v_mfma_f32_16x16x32_bf16 v[78:81], v[168:171], v[204:207], v[78:81]
	v_mfma_f32_16x16x32_bf16 v[70:73], v[146:149], v[212:215], v[70:73]
	v_mfma_f32_16x16x32_bf16 v[66:69], v[168:171], v[212:215], v[66:69]
	v_mfma_f32_16x16x32_bf16 v[110:113], v[162:165], v[186:189], v[110:113]
	v_mfma_f32_16x16x32_bf16 v[106:109], v[172:175], v[186:189], v[106:109]
	v_mfma_f32_16x16x32_bf16 v[102:105], v[162:165], v[200:203], v[102:105]
	v_mfma_f32_16x16x32_bf16 v[98:101], v[172:175], v[200:203], v[98:101]
	v_mfma_f32_16x16x32_bf16 v[86:89], v[162:165], v[208:211], v[86:89]
	v_mfma_f32_16x16x32_bf16 v[78:81], v[172:175], v[208:211], v[78:81]
	v_mfma_f32_16x16x32_bf16 v[70:73], v[162:165], v[216:219], v[70:73]
	v_mfma_f32_16x16x32_bf16 v[66:69], v[172:175], v[216:219], v[66:69]
	s_barrier
	s_add_i32 s30, s59, s34
	s_add_i32 m0, s30, 0xffffff80
	ds_read_b128 v[182:185], v180 offset:49152
	ds_read_b128 v[186:189], v180 offset:50176
	ds_read_b128 v[190:193], v180 offset:51200
	ds_read_b128 v[200:203], v180 offset:52224
	ds_read_b128 v[204:207], v180 offset:53248
	ds_read_b128 v[208:211], v180 offset:54272
	ds_read_b128 v[212:215], v180 offset:55296
	ds_read_b128 v[216:219], v180 offset:56320
	global_load_lds_dwordx4 v158, s[28:29] offset:128
	s_add_i32 m0, s30, 0x1f80
	s_add_i32 s30, s60, s34
	global_load_lds_dwordx4 v150, s[28:29] offset:128
	s_add_u32 s28, s28, 0x200080
	s_addc_u32 s29, s29, 0
	s_mov_b32 m0, s30
	s_nop 0
	global_load_lds_dwordx4 v158, s[28:29]
	s_add_i32 m0, s30, 0x2000
	s_nop 0
	global_load_lds_dwordx4 v150, s[28:29]
	s_waitcnt vmcnt(6)
	s_waitcnt lgkmcnt(0)
	s_barrier
	v_mfma_f32_16x16x32_bf16 v[62:65], v[130:133], v[182:185], v[62:65]
	v_mfma_f32_16x16x32_bf16 v[58:61], v[138:141], v[182:185], v[58:61]
	v_mfma_f32_16x16x32_bf16 v[50:53], v[130:133], v[190:193], v[50:53]
	v_mfma_f32_16x16x32_bf16 v[42:45], v[138:141], v[190:193], v[42:45]
	v_mfma_f32_16x16x32_bf16 v[34:37], v[130:133], v[204:207], v[34:37]
	v_mfma_f32_16x16x32_bf16 v[26:29], v[138:141], v[204:207], v[26:29]
	v_mfma_f32_16x16x32_bf16 v[18:21], v[130:133], v[212:215], v[18:21]
	v_mfma_f32_16x16x32_bf16 v[10:13], v[138:141], v[212:215], v[10:13]
	v_mfma_f32_16x16x32_bf16 v[62:65], v[134:137], v[186:189], v[62:65]
	v_mfma_f32_16x16x32_bf16 v[58:61], v[142:145], v[186:189], v[58:61]
	v_mfma_f32_16x16x32_bf16 v[50:53], v[134:137], v[200:203], v[50:53]
	v_mfma_f32_16x16x32_bf16 v[42:45], v[142:145], v[200:203], v[42:45]
	v_mfma_f32_16x16x32_bf16 v[34:37], v[134:137], v[208:211], v[34:37]
	v_mfma_f32_16x16x32_bf16 v[26:29], v[142:145], v[208:211], v[26:29]
	v_mfma_f32_16x16x32_bf16 v[18:21], v[134:137], v[216:219], v[18:21]
	v_mfma_f32_16x16x32_bf16 v[10:13], v[142:145], v[216:219], v[10:13]
	v_mfma_f32_16x16x32_bf16 v[54:57], v[146:149], v[182:185], v[54:57]
	v_mfma_f32_16x16x32_bf16 v[46:49], v[168:171], v[182:185], v[46:49]
	v_mfma_f32_16x16x32_bf16 v[38:41], v[146:149], v[190:193], v[38:41]
	v_mfma_f32_16x16x32_bf16 v[30:33], v[168:171], v[190:193], v[30:33]
	v_mfma_f32_16x16x32_bf16 v[22:25], v[146:149], v[204:207], v[22:25]
	v_mfma_f32_16x16x32_bf16 v[14:17], v[168:171], v[204:207], v[14:17]
	v_mfma_f32_16x16x32_bf16 v[6:9], v[146:149], v[212:215], v[6:9]
	v_mfma_f32_16x16x32_bf16 v[2:5], v[168:171], v[212:215], v[2:5]
	v_mfma_f32_16x16x32_bf16 v[54:57], v[162:165], v[186:189], v[54:57]
	v_mfma_f32_16x16x32_bf16 v[46:49], v[172:175], v[186:189], v[46:49]
	v_mfma_f32_16x16x32_bf16 v[38:41], v[162:165], v[200:203], v[38:41]
	v_mfma_f32_16x16x32_bf16 v[30:33], v[172:175], v[200:203], v[30:33]
	v_mfma_f32_16x16x32_bf16 v[22:25], v[162:165], v[208:211], v[22:25]
	v_mfma_f32_16x16x32_bf16 v[14:17], v[172:175], v[208:211], v[14:17]
	v_mfma_f32_16x16x32_bf16 v[6:9], v[162:165], v[216:219], v[6:9]
	v_mfma_f32_16x16x32_bf16 v[2:5], v[172:175], v[216:219], v[2:5]
	s_barrier
	s_add_i32 s58, s58, 2
	s_add_u32 s0, s0, 0x100
	s_addc_u32 s1, s1, 0
	s_add_u32 s56, s56, 0x100
	s_addc_u32 s57, s57, 0
	s_cmpk_gt_u32 s58, 0x7d
	s_cbranch_scc0 .LBB0_880
	s_and_b64 vcc, exec, s[14:15]
	s_cbranch_vccz .LBB0_883
	s_barrier
